# cache-policy: nt also on the read-once loads of the prologue (f32 inputs/weights) and of the branch-merge pass
# speedup vs baseline: 1.0262x; 1.0128x over previous
; __device__ __forceinline__ float shx(float v, int m, int lane) { return __builtin_bit_cast(float, __builtin_amdgcn_ds_bpermute((lane ^ m) << 2, __builtin_bit_cast(int, v))); }
; #define LAS __attribute__((address_space(3)))
; __device__ __forceinline__ float shx(float v, int m, int lane) { return __builtin_bit_cast(float, __builtin_amdgcn_ds_bpermute((lane ^ m) << 2, __builtin_bit_cast(int, v))); }
; __device__ __forceinline__ void p0_transpose_item(const float* W, int K, int N, u16* WT, LAS float* scr, int item, int lane, const float* gk = nullptr, const float* bk = nullptr, float* c1 = nullptr, float* c2 = nullptr) {
;     const int nblk = N / 32, kb = item / nblk, nb = item % nblk, k0 = 64 * kb, n0 = 32 * nb;
; #pragma unroll 8
;     for (int i = 0; i < 32; ++i) { const int kk = 2 * i + (lane >> 5); scr[kk * 33 + (lane & 31)] = W[(size_t)(k0 + kk) * N + n0 + (lane & 31)]; }
;     asm volatile("s_waitcnt lgkmcnt(0)" ::: "memory");
;     const int c = lane & 7;
;     float gs[8];
; #pragma unroll
;     for (int e = 0; e < 8; ++e) gs[e] = gk ? gk[k0 + 8 * c + e] : 1.f;
;     if (gk) {
;         const int n = lane & 31, kh = (lane >> 5) * 32; float s1 = 0.f, s2 = 0.f;
; #pragma unroll 8
;         for (int kk = 0; kk < 32; ++kk) { const float wv = scr[(kh + kk) * 33 + n]; s1 += gk[k0 + kh + kk] * wv; s2 += bk[k0 + kh + kk] * wv; }
;         s1 += shx(s1, 32, lane); s2 += shx(s2, 32, lane);
;         if (lane < 32) { atomicAdd(c1 + n0 + n, s1); atomicAdd(c2 + n0 + n, s2); }
;     }
.LBB0_16:
	s_lshl_b32 s16, s2, 1
	s_lshl_b32 s17, s3, 1
	v_or_b32_e32 v4, s17, v30
	s_add_i32 s31, s16, 4
	s_add_i32 s33, s17, 4
	v_mov_b32_e32 v35, v5
	s_add_i32 s35, s17, 8
	v_lshlrev_b64 v[58:59], 12, v[4:5]
	v_or_b32_e32 v34, s31, v3
	v_or_b32_e32 v4, s33, v30
	v_mov_b32_e32 v33, v5
	v_or_b32_e32 v32, s16, v3
	s_add_i32 s37, s17, 12
	v_lshlrev_b64 v[34:35], 12, v[34:35]
	v_lshlrev_b64 v[60:61], 12, v[4:5]
	v_or_b32_e32 v4, s35, v30
	s_add_i32 s34, s16, 8
	s_add_i32 s36, s16, 12
	s_add_i32 s39, s17, 16
	v_lshlrev_b64 v[32:33], 12, v[32:33]
	v_lshl_add_u64 v[58:59], v[28:29], 0, v[58:59]
	v_lshl_add_u64 v[34:35], v[28:29], 0, v[34:35]
	v_lshlrev_b64 v[62:63], 12, v[4:5]
	v_or_b32_e32 v4, s37, v30
	v_mov_b32_e32 v37, v5
	v_mov_b32_e32 v39, v5
	s_add_i32 s41, s17, 20
	v_or_b32_e32 v36, s34, v3
	v_or_b32_e32 v38, s36, v3
	v_lshl_add_u64 v[32:33], v[28:29], 0, v[32:33]
	v_lshl_add_u64 v[60:61], v[28:29], 0, v[60:61]
	global_load_dword v27, v[58:59], off nt
	global_load_dword v31, v[32:33], off nt
	global_load_dword v74, v[60:61], off nt
	global_load_dword v75, v[34:35], off nt
	v_lshlrev_b64 v[34:35], 12, v[4:5]
	v_or_b32_e32 v4, s39, v30
	s_add_i32 s38, s16, 16
	s_add_i32 s40, s16, 20
	s_add_i32 s43, s17, 24
	v_lshlrev_b64 v[36:37], 12, v[36:37]
	v_lshlrev_b64 v[38:39], 12, v[38:39]
	v_lshl_add_u64 v[32:33], v[28:29], 0, v[62:63]
	v_lshl_add_u64 v[34:35], v[28:29], 0, v[34:35]
	v_lshlrev_b64 v[58:59], 12, v[4:5]
	v_or_b32_e32 v4, s41, v30
	v_mov_b32_e32 v41, v5
	v_mov_b32_e32 v53, v5
	s_add_i32 s42, s16, 24
	s_add_i32 s44, s16, 28
	s_add_i32 s45, s17, 28
	v_or_b32_e32 v40, s38, v3
	v_or_b32_e32 v52, s40, v3
	v_lshl_add_u64 v[36:37], v[28:29], 0, v[36:37]
	v_lshl_add_u64 v[38:39], v[28:29], 0, v[38:39]
	global_load_dword v76, v[32:33], off nt
	global_load_dword v77, v[36:37], off nt
	global_load_dword v78, v[34:35], off nt
	global_load_dword v79, v[38:39], off nt
	v_lshlrev_b64 v[34:35], 12, v[4:5]
	v_or_b32_e32 v4, s43, v30
	v_mov_b32_e32 v55, v5
	v_mov_b32_e32 v57, v5
	v_or_b32_e32 v54, s42, v3
	v_or_b32_e32 v56, s44, v3
	v_lshlrev_b64 v[40:41], 12, v[40:41]
	v_lshlrev_b64 v[52:53], 12, v[52:53]
	v_lshl_add_u64 v[32:33], v[28:29], 0, v[58:59]
	v_lshl_add_u64 v[34:35], v[28:29], 0, v[34:35]
	v_lshlrev_b64 v[36:37], 12, v[4:5]
	v_or_b32_e32 v4, s45, v30
	v_lshlrev_b64 v[54:55], 12, v[54:55]
	v_lshlrev_b64 v[56:57], 12, v[56:57]
	v_lshl_add_u64 v[40:41], v[28:29], 0, v[40:41]
	v_lshl_add_u64 v[52:53], v[28:29], 0, v[52:53]
	global_load_dword v80, v[32:33], off nt
	global_load_dword v81, v[40:41], off nt
	global_load_dword v82, v[34:35], off nt
	global_load_dword v83, v[52:53], off nt
	v_lshl_add_u64 v[32:33], v[28:29], 0, v[36:37]
	v_lshlrev_b64 v[34:35], 12, v[4:5]
	v_lshl_add_u64 v[54:55], v[28:29], 0, v[54:55]
	v_lshl_add_u64 v[56:57], v[28:29], 0, v[56:57]
	v_lshl_add_u64 v[34:35], v[28:29], 0, v[34:35]
	global_load_dword v4, v[32:33], off nt
	global_load_dword v84, v[54:55], off nt
	global_load_dword v85, v[34:35], off nt
	global_load_dword v86, v[56:57], off nt
	v_or_b32_e32 v34, s16, v1
	v_or_b32_e32 v32, s17, v2
	s_add_i32 s3, s3, 16
	s_add_i32 s2, s2, 16
	s_add_i32 s12, s12, -16
	v_mad_u64_u32 v[32:33], s[16:17], v32, s26, v[6:7]
	v_mad_u64_u32 v[34:35], s[16:17], v34, s26, v[6:7]
	v_or_b32_e32 v33, s31, v1
	v_or_b32_e32 v35, s33, v2
	v_or_b32_e32 v52, s34, v1
	v_or_b32_e32 v40, s35, v2
	v_or_b32_e32 v56, s36, v1
	v_or_b32_e32 v54, s37, v2
	v_or_b32_e32 v60, s38, v1
	v_or_b32_e32 v58, s39, v2
	v_or_b32_e32 v64, s40, v1
	v_or_b32_e32 v62, s41, v2
	v_or_b32_e32 v68, s42, v1
	v_or_b32_e32 v66, s43, v2
	v_or_b32_e32 v72, s44, v1
	v_or_b32_e32 v70, s45, v2
	s_cmp_lg_u32 s12, 0
	v_mad_u64_u32 v[36:37], s[16:17], v35, s26, v[6:7]
	v_mad_u64_u32 v[38:39], s[16:17], v33, s26, v[6:7]
	v_mad_u64_u32 v[40:41], s[16:17], v40, s26, v[6:7]
	v_mad_u64_u32 v[52:53], s[16:17], v52, s26, v[6:7]
	v_mad_u64_u32 v[54:55], s[16:17], v54, s26, v[6:7]
	v_mad_u64_u32 v[56:57], s[16:17], v56, s26, v[6:7]
	v_mad_u64_u32 v[58:59], s[16:17], v58, s26, v[6:7]
	v_mad_u64_u32 v[60:61], s[16:17], v60, s26, v[6:7]
	v_mad_u64_u32 v[62:63], s[16:17], v62, s26, v[6:7]
	v_mad_u64_u32 v[64:65], s[16:17], v64, s26, v[6:7]
	v_mad_u64_u32 v[66:67], s[16:17], v66, s26, v[6:7]
	v_mad_u64_u32 v[68:69], s[16:17], v68, s26, v[6:7]
	v_mad_u64_u32 v[70:71], s[16:17], v70, s26, v[6:7]
	v_mad_u64_u32 v[72:73], s[16:17], v72, s26, v[6:7]
	s_waitcnt vmcnt(15)
	ds_write_b32 v32, v27
	s_waitcnt vmcnt(14)
	ds_write_b32 v34, v31
	s_waitcnt vmcnt(13)
	ds_write_b32 v36, v74
	s_waitcnt vmcnt(12)
	ds_write_b32 v38, v75
	s_waitcnt vmcnt(11)
	ds_write_b32 v40, v76
	s_waitcnt vmcnt(10)
	ds_write_b32 v52, v77
	s_waitcnt vmcnt(9)
	ds_write_b32 v54, v78
	s_waitcnt vmcnt(8)
	ds_write_b32 v56, v79
	s_waitcnt vmcnt(7)
	ds_write_b32 v58, v80
	s_waitcnt vmcnt(6)
	ds_write_b32 v60, v81
	s_waitcnt vmcnt(5)
	ds_write_b32 v62, v82
	s_waitcnt vmcnt(4)
	ds_write_b32 v64, v83
	s_waitcnt vmcnt(3)
	ds_write_b32 v66, v4
	s_waitcnt vmcnt(2)
	ds_write_b32 v68, v84
	s_waitcnt vmcnt(1)
	ds_write_b32 v70, v85
	s_waitcnt vmcnt(0)
	ds_write_b32 v72, v86
	s_cbranch_scc1 .LBB0_16
	s_lshl_b32 s12, s14, 10
	v_readlane_b32 s36, v253, 9
	s_lshl_b64 s[2:3], s[12:13], 2
	v_readlane_b32 s48, v253, 21
	s_waitcnt lgkmcnt(0)
	v_readlane_b32 s49, v253, 22
	s_add_u32 s16, s48, s2
	v_or_b32_e32 v3, s30, v8
	s_addc_u32 s17, s49, s3
	v_mov_b32_e32 v29, 1.0
	v_cmp_ne_u32_e64 s[2:3], 1, v51
	s_andn2_b64 vcc, exec, s[8:9]
	v_lshlrev_b32_e32 v3, 2, v3
	v_mov_b32_e32 v28, 1.0
	v_readlane_b32 s37, v253, 10
	v_readlane_b32 s38, v253, 11
	v_readlane_b32 s39, v253, 12
	v_readlane_b32 s40, v253, 13
	v_readlane_b32 s41, v253, 14
	v_readlane_b32 s42, v253, 15
	v_readlane_b32 s43, v253, 16
	v_readlane_b32 s44, v253, 17
	v_readlane_b32 s45, v253, 18
	v_readlane_b32 s46, v253, 19
	v_readlane_b32 s47, v253, 20
	v_readlane_b32 s50, v253, 23
	v_readlane_b32 s51, v253, 24
	s_cbranch_vccnz .LBB0_19
	global_load_dword v28, v3, s[16:17] nt
.LBB0_19:
	s_and_b64 vcc, exec, s[2:3]
	s_cbranch_vccnz .LBB0_21
	global_load_dword v29, v3, s[16:17] offset:4 nt
.LBB0_21:
	v_mov_b32_e32 v31, 1.0
	s_and_b64 vcc, exec, s[2:3]
	v_mov_b32_e32 v30, 1.0
	s_cbranch_vccnz .LBB0_23
	global_load_dword v30, v3, s[16:17] offset:8 nt
.LBB0_23:
	s_and_b64 vcc, exec, s[2:3]
	s_cbranch_vccnz .LBB0_25
	global_load_dword v31, v3, s[16:17] offset:12 nt
.LBB0_25:
	v_mov_b32_e32 v33, 1.0
	s_and_b64 vcc, exec, s[2:3]
	v_mov_b32_e32 v32, 1.0
	s_cbranch_vccnz .LBB0_27
	global_load_dword v32, v3, s[16:17] offset:16 nt
.LBB0_27:
	s_and_b64 vcc, exec, s[2:3]
	s_cbranch_vccnz .LBB0_29
	global_load_dword v33, v3, s[16:17] offset:20 nt
.LBB0_29:
	v_mov_b32_e32 v35, 1.0
	s_and_b64 vcc, exec, s[2:3]
	v_mov_b32_e32 v34, 1.0
	s_cbranch_vccnz .LBB0_31
	global_load_dword v34, v3, s[16:17] offset:24 nt
.LBB0_31:
	s_and_b64 vcc, exec, s[2:3]
	s_cbranch_vccnz .LBB0_33
	global_load_dword v35, v3, s[16:17] offset:28 nt

; __device__ __forceinline__ float shx(float v, int m, int lane) { return __builtin_bit_cast(float, __builtin_amdgcn_ds_bpermute((lane ^ m) << 2, __builtin_bit_cast(int, v))); }
; __device__ __forceinline__ float shx(float v, int m, int lane) { return __builtin_bit_cast(float, __builtin_amdgcn_ds_bpermute((lane ^ m) << 2, __builtin_bit_cast(int, v))); }
; __device__ __forceinline__ void p0_transpose_item(const float* W, int K, int N, u16* WT, LAS float* scr, int item, int lane, const float* gk = nullptr, const float* bk = nullptr, float* c1 = nullptr, float* c2 = nullptr) {
;     ...
;     if (gk) {
;         const int n = lane & 31, kh = (lane >> 5) * 32; float s1 = 0.f, s2 = 0.f;
; #pragma unroll 8
;         for (int kk = 0; kk < 32; ++kk) { const float wv = scr[(kh + kk) * 33 + n]; s1 += gk[k0 + kh + kk] * wv; s2 += bk[k0 + kh + kk] * wv; }
;         s1 += shx(s1, 32, lane); s2 += shx(s2, 32, lane);
;         if (lane < 32) { atomicAdd(c1 + n0 + n, s1); atomicAdd(c2 + n0 + n, s2); }
;     }
.LBB0_35:
	v_lshl_add_u64 v[60:61], v[38:39], 0, s[2:3]
	v_lshl_add_u64 v[64:65], v[40:41], 0, s[2:3]
	global_load_dwordx4 v[52:55], v[60:61], off nt
	global_load_dwordx4 v[56:59], v[64:65], off nt
	s_nop 0
	global_load_dwordx4 v[60:63], v[60:61], off offset:16 nt
	s_nop 0
	global_load_dwordx4 v[64:67], v[64:65], off offset:16 nt
	ds_read2_b32 v[68:69], v3 offset1:33
	ds_read2_b32 v[70:71], v3 offset0:66 offset1:99
	ds_read2_b32 v[72:73], v3 offset0:132 offset1:165
	ds_read2_b32 v[74:75], v3 offset0:198 offset1:231
	s_add_u32 s2, s2, 32
	s_waitcnt lgkmcnt(3)
	v_mov_b32_e32 v4, v69
	s_waitcnt lgkmcnt(2)
	v_mov_b32_e32 v76, v71
	s_waitcnt lgkmcnt(1)
	v_mov_b32_e32 v78, v73
	s_addc_u32 s3, s3, 0
	s_waitcnt lgkmcnt(0)
	v_mov_b32_e32 v80, v75
	v_add_u32_e32 v3, 0x420, v3
	s_cmpk_eq_i32 s2, 0x80
	s_waitcnt vmcnt(3)
	v_mov_b32_e32 v82, v52
	s_waitcnt vmcnt(2)
	v_mov_b32_e32 v83, v56
	v_mov_b32_e32 v56, v53
	v_pk_fma_f32 v[36:37], v[68:69], v[82:83], v[36:37] op_sel_hi:[0,1,1]
	v_mov_b32_e32 v52, v54
	v_mov_b32_e32 v53, v58
	v_pk_fma_f32 v[36:37], v[4:5], v[56:57], v[36:37] op_sel_hi:[0,1,1]
	v_mov_b32_e32 v58, v55
	v_pk_fma_f32 v[36:37], v[70:71], v[52:53], v[36:37] op_sel_hi:[0,1,1]
	s_waitcnt vmcnt(1)
	v_mov_b32_e32 v54, v60
	s_waitcnt vmcnt(0)
	v_mov_b32_e32 v55, v64
	v_pk_fma_f32 v[36:37], v[76:77], v[58:59], v[36:37] op_sel_hi:[0,1,1]
	v_mov_b32_e32 v64, v61
	v_pk_fma_f32 v[36:37], v[72:73], v[54:55], v[36:37] op_sel_hi:[0,1,1]
	v_mov_b32_e32 v60, v62
	v_mov_b32_e32 v61, v66
	v_pk_fma_f32 v[36:37], v[78:79], v[64:65], v[36:37] op_sel_hi:[0,1,1]
	v_mov_b32_e32 v66, v63
	v_pk_fma_f32 v[36:37], v[74:75], v[60:61], v[36:37] op_sel_hi:[0,1,1]
	v_pk_fma_f32 v[36:37], v[80:81], v[66:67], v[36:37] op_sel_hi:[0,1,1]
	s_cbranch_scc0 .LBB0_35
	ds_bpermute_b32 v3, v9, v36
	ds_bpermute_b32 v4, v9, v37
	s_and_saveexec_b64 s[2:3], s[0:1]
	s_cbranch_execz .LBB0_38
	s_mul_i32 s12, s14, 0x2800
	s_lshl_b64 s[16:17], s[12:13], 2
	s_add_u32 s12, s62, s16
	s_addc_u32 s17, s63, s17
	s_lshl_b32 s16, s15, 2
	s_add_u32 s16, s12, s16
	v_mov_b32_e32 v27, v5
	s_addc_u32 s17, s17, 0
	v_lshl_add_u64 v[38:39], s[16:17], 0, v[26:27]
	s_waitcnt lgkmcnt(1)
	v_add_f32_e32 v3, v36, v3
	v_add_co_u32_e32 v36, vcc, 0x8000, v38
	s_waitcnt lgkmcnt(0)
	v_add_f32_e32 v4, v37, v4
	v_addc_co_u32_e32 v37, vcc, 0, v39, vcc
	global_atomic_add_f32 v[36:37], v3, off
	v_add_co_u32_e32 v36, vcc, 0x9000, v38
	s_nop 1
	v_addc_co_u32_e32 v37, vcc, 0, v39, vcc
	global_atomic_add_f32 v[36:37], v4, off

; #define LAS __attribute__((address_space(3)))
; __device__ __forceinline__ void p0_transpose_item(const float* W, int K, int N, u16* WT, LAS float* scr, int item, int lane, const float* gk = nullptr, const float* bk = nullptr, float* c1 = nullptr, float* c2 = nullptr) {
;     const int nblk = N / 32, kb = item / nblk, nb = item % nblk, k0 = 64 * kb, n0 = 32 * nb;
; #pragma unroll 8
;     for (int i = 0; i < 32; ++i) { const int kk = 2 * i + (lane >> 5); scr[kk * 33 + (lane & 31)] = W[(size_t)(k0 + kk) * N + n0 + (lane & 31)]; }
;     asm volatile("s_waitcnt lgkmcnt(0)" ::: "memory");
.LBB0_42:
	s_lshl_b32 s17, s14, 1
	s_lshl_b32 s30, s15, 1
	v_or_b32_e32 v4, s30, v30
	s_add_i32 s33, s17, 4
	s_add_i32 s34, s30, 4
	v_mov_b32_e32 v35, v5
	s_add_i32 s36, s30, 8
	v_lshlrev_b64 v[58:59], 12, v[4:5]
	v_or_b32_e32 v34, s33, v3
	v_or_b32_e32 v4, s34, v30
	v_mov_b32_e32 v33, v5
	v_or_b32_e32 v32, s17, v3
	s_add_i32 s38, s30, 12
	v_lshlrev_b64 v[34:35], 12, v[34:35]
	v_lshlrev_b64 v[60:61], 12, v[4:5]
	v_or_b32_e32 v4, s36, v30
	s_add_i32 s35, s17, 8
	s_add_i32 s37, s17, 12
	s_add_i32 s40, s30, 16
	v_lshlrev_b64 v[32:33], 12, v[32:33]
	v_lshl_add_u64 v[58:59], v[28:29], 0, v[58:59]
	v_lshl_add_u64 v[34:35], v[28:29], 0, v[34:35]
	v_lshlrev_b64 v[62:63], 12, v[4:5]
	v_or_b32_e32 v4, s38, v30
	v_mov_b32_e32 v37, v5
	v_mov_b32_e32 v39, v5
	s_add_i32 s42, s30, 20
	v_or_b32_e32 v36, s35, v3
	v_or_b32_e32 v38, s37, v3
	v_lshl_add_u64 v[32:33], v[28:29], 0, v[32:33]
	v_lshl_add_u64 v[60:61], v[28:29], 0, v[60:61]
	global_load_dword v27, v[58:59], off nt
	global_load_dword v31, v[32:33], off nt
	global_load_dword v74, v[60:61], off nt
	global_load_dword v75, v[34:35], off nt
	v_lshlrev_b64 v[34:35], 12, v[4:5]
	v_or_b32_e32 v4, s40, v30
	s_add_i32 s39, s17, 16
	s_add_i32 s41, s17, 20
	s_add_i32 s44, s30, 24
	v_lshlrev_b64 v[36:37], 12, v[36:37]
	v_lshlrev_b64 v[38:39], 12, v[38:39]
	v_lshl_add_u64 v[32:33], v[28:29], 0, v[62:63]
	v_lshl_add_u64 v[34:35], v[28:29], 0, v[34:35]
	v_lshlrev_b64 v[58:59], 12, v[4:5]
	v_or_b32_e32 v4, s42, v30
	v_mov_b32_e32 v41, v5
	v_mov_b32_e32 v53, v5
	s_add_i32 s43, s17, 24
	s_add_i32 s45, s17, 28
	s_add_i32 s46, s30, 28
	v_or_b32_e32 v40, s39, v3
	v_or_b32_e32 v52, s41, v3
	v_lshl_add_u64 v[36:37], v[28:29], 0, v[36:37]
	v_lshl_add_u64 v[38:39], v[28:29], 0, v[38:39]
	global_load_dword v76, v[32:33], off nt
	global_load_dword v77, v[36:37], off nt
	global_load_dword v78, v[34:35], off nt
	global_load_dword v79, v[38:39], off nt
	v_lshlrev_b64 v[34:35], 12, v[4:5]
	v_or_b32_e32 v4, s44, v30
	v_mov_b32_e32 v55, v5
	v_mov_b32_e32 v57, v5
	v_or_b32_e32 v54, s43, v3
	v_or_b32_e32 v56, s45, v3
	v_lshlrev_b64 v[40:41], 12, v[40:41]
	v_lshlrev_b64 v[52:53], 12, v[52:53]
	v_lshl_add_u64 v[32:33], v[28:29], 0, v[58:59]
	v_lshl_add_u64 v[34:35], v[28:29], 0, v[34:35]
	v_lshlrev_b64 v[36:37], 12, v[4:5]
	v_or_b32_e32 v4, s46, v30
	v_lshlrev_b64 v[54:55], 12, v[54:55]
	v_lshlrev_b64 v[56:57], 12, v[56:57]
	v_lshl_add_u64 v[40:41], v[28:29], 0, v[40:41]
	v_lshl_add_u64 v[52:53], v[28:29], 0, v[52:53]
	global_load_dword v80, v[32:33], off nt
	global_load_dword v81, v[40:41], off nt
	global_load_dword v82, v[34:35], off nt
	global_load_dword v83, v[52:53], off nt
	v_lshl_add_u64 v[32:33], v[28:29], 0, v[36:37]
	v_lshlrev_b64 v[34:35], 12, v[4:5]
	v_lshl_add_u64 v[54:55], v[28:29], 0, v[54:55]
	v_lshl_add_u64 v[56:57], v[28:29], 0, v[56:57]
	v_lshl_add_u64 v[34:35], v[28:29], 0, v[34:35]
	global_load_dword v4, v[32:33], off nt
	global_load_dword v84, v[54:55], off nt
	global_load_dword v85, v[34:35], off nt
	global_load_dword v86, v[56:57], off nt
	v_or_b32_e32 v34, s17, v1
	v_or_b32_e32 v32, s30, v2
	s_add_i32 s15, s15, 16
	s_add_i32 s14, s14, 16
	s_add_i32 s16, s16, -16
	v_mad_u64_u32 v[32:33], s[30:31], v32, s26, v[6:7]
	v_mad_u64_u32 v[34:35], s[30:31], v34, s26, v[6:7]
	v_or_b32_e32 v33, s33, v1
	v_or_b32_e32 v35, s34, v2
	v_or_b32_e32 v52, s35, v1
	v_or_b32_e32 v40, s36, v2
	v_or_b32_e32 v56, s37, v1
	v_or_b32_e32 v54, s38, v2
	v_or_b32_e32 v60, s39, v1
	v_or_b32_e32 v58, s40, v2
	v_or_b32_e32 v64, s41, v1
	v_or_b32_e32 v62, s42, v2
	v_or_b32_e32 v68, s43, v1
	v_or_b32_e32 v66, s44, v2
	v_or_b32_e32 v72, s45, v1
	v_or_b32_e32 v70, s46, v2
	s_cmp_lg_u32 s16, 0
	v_mad_u64_u32 v[36:37], s[30:31], v35, s26, v[6:7]
	v_mad_u64_u32 v[38:39], s[30:31], v33, s26, v[6:7]
	v_mad_u64_u32 v[40:41], s[30:31], v40, s26, v[6:7]
	v_mad_u64_u32 v[52:53], s[30:31], v52, s26, v[6:7]
	v_mad_u64_u32 v[54:55], s[30:31], v54, s26, v[6:7]
	v_mad_u64_u32 v[56:57], s[30:31], v56, s26, v[6:7]
	v_mad_u64_u32 v[58:59], s[30:31], v58, s26, v[6:7]
	v_mad_u64_u32 v[60:61], s[30:31], v60, s26, v[6:7]
	v_mad_u64_u32 v[62:63], s[30:31], v62, s26, v[6:7]
	v_mad_u64_u32 v[64:65], s[30:31], v64, s26, v[6:7]
	v_mad_u64_u32 v[66:67], s[30:31], v66, s26, v[6:7]
	v_mad_u64_u32 v[68:69], s[30:31], v68, s26, v[6:7]
	v_mad_u64_u32 v[70:71], s[30:31], v70, s26, v[6:7]
	v_mad_u64_u32 v[72:73], s[30:31], v72, s26, v[6:7]
	s_waitcnt vmcnt(15)
	ds_write_b32 v32, v27
	s_waitcnt vmcnt(14)
	ds_write_b32 v34, v31
	s_waitcnt vmcnt(13)
	ds_write_b32 v36, v74
	s_waitcnt vmcnt(12)
	ds_write_b32 v38, v75
	s_waitcnt vmcnt(11)
	ds_write_b32 v40, v76
	s_waitcnt vmcnt(10)
	ds_write_b32 v52, v77
	s_waitcnt vmcnt(9)
	ds_write_b32 v54, v78
	s_waitcnt vmcnt(8)
	ds_write_b32 v56, v79
	s_waitcnt vmcnt(7)
	ds_write_b32 v58, v80
	s_waitcnt vmcnt(6)
	ds_write_b32 v60, v81
	s_waitcnt vmcnt(5)
	ds_write_b32 v62, v82
	s_waitcnt vmcnt(4)
	ds_write_b32 v64, v83
	s_waitcnt vmcnt(3)
	ds_write_b32 v66, v4
	s_waitcnt vmcnt(2)
	ds_write_b32 v68, v84
	s_waitcnt vmcnt(1)
	ds_write_b32 v70, v85
	s_waitcnt vmcnt(0)
	ds_write_b32 v72, v86
	s_cbranch_scc1 .LBB0_42
; #define LAS __attribute__((address_space(3)))
; __device__ __forceinline__ unsigned pk2(float lo, float hi) { f32x2_t v = {lo, hi}; bf16x2_t b = __builtin_convertvector(v, bf16x2_t); return __builtin_bit_cast(unsigned, b); }
; __device__ __forceinline__ void p0_transpose_item(const float* W, int K, int N, u16* WT, LAS float* scr, int item, int lane, const float* gk = nullptr, const float* bk = nullptr, float* c1 = nullptr, float* c2 = nullptr) {
;     ...
; #pragma unroll
;     for (int j = 0; j < 4; ++j) { const int n = (lane >> 3) + 8 * j; const LAS float* sp = scr + (8 * c) * 33 + n;
;         v4u o; o.x = pk2(sp[0 * 33] * gs[0], sp[1 * 33] * gs[1]); o.y = pk2(sp[2 * 33] * gs[2], sp[3 * 33] * gs[3]); o.z = pk2(sp[4 * 33] * gs[4], sp[5 * 33] * gs[5]); o.w = pk2(sp[6 * 33] * gs[6], sp[7 * 33] * gs[7]);
;         *(v4u*)(WT + (size_t)(n0 + n) * K + k0 + 8 * c) = o; }
;     asm volatile("s_waitcnt lgkmcnt(0)" ::: "memory");
	s_lshl_b64 s[14:15], s[12:13], 19
	v_readlane_b32 s12, v253, 28
	s_waitcnt lgkmcnt(0)
	s_add_u32 s12, s12, s14
	v_readlane_b32 s14, v253, 29
	ds_read2_b32 v[32:33], v46 offset0:33 offset1:41
	ds_read2_b32 v[34:35], v46 offset1:8
	ds_read2_b32 v[36:37], v46 offset0:66 offset1:74
	ds_read2_b32 v[38:39], v46 offset0:99 offset1:107
	ds_read2_b32 v[40:41], v46 offset0:132 offset1:140
	ds_read2_b32 v[52:53], v46 offset0:165 offset1:173
	ds_read2_b32 v[54:55], v46 offset0:198 offset1:206
	ds_read2_b32 v[56:57], v46 offset0:231 offset1:239
	s_addc_u32 s15, s14, s15
	s_lshl_b32 s3, s3, 1
	s_add_u32 s14, s12, s3
	s_addc_u32 s15, s15, 0
	v_lshlrev_b32_e32 v4, 1, v8
	v_or_b32_e32 v3, s2, v45
	v_lshl_add_u64 v[58:59], s[14:15], 0, v[4:5]
	v_lshlrev_b32_e32 v4, 9, v3
	s_waitcnt lgkmcnt(6)
	v_cvt_pk_bf16_f32 v28, v34, v32
	s_waitcnt lgkmcnt(4)
	v_cvt_pk_bf16_f32 v29, v36, v38
	s_waitcnt lgkmcnt(2)
	v_cvt_pk_bf16_f32 v30, v40, v52
	s_waitcnt lgkmcnt(0)
	v_cvt_pk_bf16_f32 v31, v54, v56
	v_lshl_add_u64 v[60:61], v[58:59], 0, v[4:5]
	global_store_dwordx4 v[60:61], v[28:31], off
	v_or_b32_e32 v3, s2, v47
	v_lshlrev_b32_e32 v4, 9, v3
	v_cvt_pk_bf16_f32 v28, v35, v33
	v_cvt_pk_bf16_f32 v29, v37, v39
	v_cvt_pk_bf16_f32 v30, v41, v53
	v_cvt_pk_bf16_f32 v31, v55, v57
	ds_read2_b32 v[34:35], v46 offset0:49 offset1:57
	ds_read2_b32 v[36:37], v46 offset0:16 offset1:24
	ds_read2_b32 v[38:39], v46 offset0:82 offset1:90
	ds_read2_b32 v[40:41], v46 offset0:115 offset1:123
	ds_read2_b32 v[52:53], v46 offset0:148 offset1:156
	ds_read2_b32 v[54:55], v46 offset0:181 offset1:189
	ds_read2_b32 v[56:57], v46 offset0:214 offset1:222
	ds_read2_b32 v[60:61], v46 offset0:247 offset1:255
	v_or_b32_e32 v3, s2, v48
	v_lshl_add_u64 v[32:33], v[58:59], 0, v[4:5]
	v_lshlrev_b32_e32 v4, 9, v3
	v_or_b32_e32 v3, s2, v49
	global_store_dwordx4 v[32:33], v[28:31], off
	v_lshl_add_u64 v[32:33], v[58:59], 0, v[4:5]
	v_lshlrev_b32_e32 v4, 9, v3
	s_waitcnt lgkmcnt(6)
	v_cvt_pk_bf16_f32 v28, v36, v34
	s_waitcnt lgkmcnt(4)
	v_cvt_pk_bf16_f32 v29, v38, v40
	s_waitcnt lgkmcnt(2)
	v_cvt_pk_bf16_f32 v30, v52, v54
	s_waitcnt lgkmcnt(0)
	v_cvt_pk_bf16_f32 v31, v56, v60
	global_store_dwordx4 v[32:33], v[28:31], off
	v_lshl_add_u64 v[32:33], v[58:59], 0, v[4:5]
	s_nop 0
	v_cvt_pk_bf16_f32 v28, v37, v35
	v_cvt_pk_bf16_f32 v29, v39, v41
	v_cvt_pk_bf16_f32 v30, v53, v55
	v_cvt_pk_bf16_f32 v31, v57, v61
	global_store_dwordx4 v[32:33], v[28:31], off
	s_waitcnt lgkmcnt(0)

; #define LAS __attribute__((address_space(3)))
; __device__ __forceinline__ void p0_transpose_item(const float* W, int K, int N, u16* WT, LAS float* scr, int item, int lane, const float* gk = nullptr, const float* bk = nullptr, float* c1 = nullptr, float* c2 = nullptr) {
;     const int nblk = N / 32, kb = item / nblk, nb = item % nblk, k0 = 64 * kb, n0 = 32 * nb;
; #pragma unroll 8
;     for (int i = 0; i < 32; ++i) { const int kk = 2 * i + (lane >> 5); scr[kk * 33 + (lane & 31)] = W[(size_t)(k0 + kk) * N + n0 + (lane & 31)]; }
;     asm volatile("s_waitcnt lgkmcnt(0)" ::: "memory");
.LBB0_47:
	s_lshl_b32 s17, s12, 1
	s_lshl_b32 s30, s15, 1
	v_or_b32_e32 v4, s30, v30
	s_add_i32 s33, s17, 4
	s_add_i32 s34, s30, 4
	v_mov_b32_e32 v35, v5
	s_add_i32 s36, s30, 8
	v_lshlrev_b64 v[58:59], 12, v[4:5]
	v_or_b32_e32 v34, s33, v3
	v_or_b32_e32 v4, s34, v30
	v_mov_b32_e32 v33, v5
	v_or_b32_e32 v32, s17, v3
	s_add_i32 s38, s30, 12
	v_lshlrev_b64 v[34:35], 12, v[34:35]
	v_lshlrev_b64 v[60:61], 12, v[4:5]
	v_or_b32_e32 v4, s36, v30
	s_add_i32 s35, s17, 8
	s_add_i32 s37, s17, 12
	s_add_i32 s40, s30, 16
	v_lshlrev_b64 v[32:33], 12, v[32:33]
	v_lshl_add_u64 v[58:59], v[28:29], 0, v[58:59]
	v_lshl_add_u64 v[34:35], v[28:29], 0, v[34:35]
	v_lshlrev_b64 v[62:63], 12, v[4:5]
	v_or_b32_e32 v4, s38, v30
	v_mov_b32_e32 v37, v5
	v_mov_b32_e32 v39, v5
	s_add_i32 s42, s30, 20
	v_or_b32_e32 v36, s35, v3
	v_or_b32_e32 v38, s37, v3
	v_lshl_add_u64 v[32:33], v[28:29], 0, v[32:33]
	v_lshl_add_u64 v[60:61], v[28:29], 0, v[60:61]
	global_load_dword v27, v[58:59], off nt
	global_load_dword v31, v[32:33], off nt
	global_load_dword v74, v[60:61], off nt
	global_load_dword v75, v[34:35], off nt
	v_lshlrev_b64 v[34:35], 12, v[4:5]
	v_or_b32_e32 v4, s40, v30
	s_add_i32 s39, s17, 16
	s_add_i32 s41, s17, 20
	s_add_i32 s44, s30, 24
	v_lshlrev_b64 v[36:37], 12, v[36:37]
	v_lshlrev_b64 v[38:39], 12, v[38:39]
	v_lshl_add_u64 v[32:33], v[28:29], 0, v[62:63]
	v_lshl_add_u64 v[34:35], v[28:29], 0, v[34:35]
	v_lshlrev_b64 v[58:59], 12, v[4:5]
	v_or_b32_e32 v4, s42, v30
	v_mov_b32_e32 v41, v5
	v_mov_b32_e32 v53, v5
	s_add_i32 s43, s17, 24
	s_add_i32 s45, s17, 28
	s_add_i32 s46, s30, 28
	v_or_b32_e32 v40, s39, v3
	v_or_b32_e32 v52, s41, v3
	v_lshl_add_u64 v[36:37], v[28:29], 0, v[36:37]
	v_lshl_add_u64 v[38:39], v[28:29], 0, v[38:39]
	global_load_dword v76, v[32:33], off nt
	global_load_dword v77, v[36:37], off nt
	global_load_dword v78, v[34:35], off nt
	global_load_dword v79, v[38:39], off nt
	v_lshlrev_b64 v[34:35], 12, v[4:5]
	v_or_b32_e32 v4, s44, v30
	v_mov_b32_e32 v55, v5
	v_mov_b32_e32 v57, v5
	v_or_b32_e32 v54, s43, v3
	v_or_b32_e32 v56, s45, v3
	v_lshlrev_b64 v[40:41], 12, v[40:41]
	v_lshlrev_b64 v[52:53], 12, v[52:53]
	v_lshl_add_u64 v[32:33], v[28:29], 0, v[58:59]
	v_lshl_add_u64 v[34:35], v[28:29], 0, v[34:35]
	v_lshlrev_b64 v[36:37], 12, v[4:5]
	v_or_b32_e32 v4, s46, v30
	v_lshlrev_b64 v[54:55], 12, v[54:55]
	v_lshlrev_b64 v[56:57], 12, v[56:57]
	v_lshl_add_u64 v[40:41], v[28:29], 0, v[40:41]
	v_lshl_add_u64 v[52:53], v[28:29], 0, v[52:53]
	global_load_dword v80, v[32:33], off nt
	global_load_dword v81, v[40:41], off nt
	global_load_dword v82, v[34:35], off nt
	global_load_dword v83, v[52:53], off nt
	v_lshl_add_u64 v[32:33], v[28:29], 0, v[36:37]
	v_lshlrev_b64 v[34:35], 12, v[4:5]
	v_lshl_add_u64 v[54:55], v[28:29], 0, v[54:55]
	v_lshl_add_u64 v[56:57], v[28:29], 0, v[56:57]
	v_lshl_add_u64 v[34:35], v[28:29], 0, v[34:35]
	global_load_dword v4, v[32:33], off nt
	global_load_dword v84, v[54:55], off nt
	global_load_dword v85, v[34:35], off nt
	global_load_dword v86, v[56:57], off nt
	v_or_b32_e32 v34, s17, v1
	v_or_b32_e32 v32, s30, v2
	s_add_i32 s15, s15, 16
	s_add_i32 s12, s12, 16
	s_add_i32 s16, s16, -16
	v_mad_u64_u32 v[32:33], s[30:31], v32, s26, v[6:7]
	v_mad_u64_u32 v[34:35], s[30:31], v34, s26, v[6:7]
	v_or_b32_e32 v33, s33, v1
	v_or_b32_e32 v35, s34, v2
	v_or_b32_e32 v52, s35, v1
	v_or_b32_e32 v40, s36, v2
	v_or_b32_e32 v56, s37, v1
	v_or_b32_e32 v54, s38, v2
	v_or_b32_e32 v60, s39, v1
	v_or_b32_e32 v58, s40, v2
	v_or_b32_e32 v64, s41, v1
	v_or_b32_e32 v62, s42, v2
	v_or_b32_e32 v68, s43, v1
	v_or_b32_e32 v66, s44, v2
	v_or_b32_e32 v72, s45, v1
	v_or_b32_e32 v70, s46, v2
	s_cmp_lg_u32 s16, 0
	v_mad_u64_u32 v[36:37], s[30:31], v35, s26, v[6:7]
	v_mad_u64_u32 v[38:39], s[30:31], v33, s26, v[6:7]
	v_mad_u64_u32 v[40:41], s[30:31], v40, s26, v[6:7]
	v_mad_u64_u32 v[52:53], s[30:31], v52, s26, v[6:7]
	v_mad_u64_u32 v[54:55], s[30:31], v54, s26, v[6:7]
	v_mad_u64_u32 v[56:57], s[30:31], v56, s26, v[6:7]
	v_mad_u64_u32 v[58:59], s[30:31], v58, s26, v[6:7]
	v_mad_u64_u32 v[60:61], s[30:31], v60, s26, v[6:7]
	v_mad_u64_u32 v[62:63], s[30:31], v62, s26, v[6:7]
	v_mad_u64_u32 v[64:65], s[30:31], v64, s26, v[6:7]
	v_mad_u64_u32 v[66:67], s[30:31], v66, s26, v[6:7]
	v_mad_u64_u32 v[68:69], s[30:31], v68, s26, v[6:7]
	v_mad_u64_u32 v[70:71], s[30:31], v70, s26, v[6:7]
	v_mad_u64_u32 v[72:73], s[30:31], v72, s26, v[6:7]
	s_waitcnt vmcnt(15)
	ds_write_b32 v32, v27
	s_waitcnt vmcnt(14)
	ds_write_b32 v34, v31
	s_waitcnt vmcnt(13)
	ds_write_b32 v36, v74
	s_waitcnt vmcnt(12)
	ds_write_b32 v38, v75
	s_waitcnt vmcnt(11)
	ds_write_b32 v40, v76
	s_waitcnt vmcnt(10)
	ds_write_b32 v52, v77
	s_waitcnt vmcnt(9)
	ds_write_b32 v54, v78
	s_waitcnt vmcnt(8)
	ds_write_b32 v56, v79
	s_waitcnt vmcnt(7)
	ds_write_b32 v58, v80
	s_waitcnt vmcnt(6)
	ds_write_b32 v60, v81
	s_waitcnt vmcnt(5)
	ds_write_b32 v62, v82
	s_waitcnt vmcnt(4)
	ds_write_b32 v64, v83
	s_waitcnt vmcnt(3)
	ds_write_b32 v66, v4
	s_waitcnt vmcnt(2)
	ds_write_b32 v68, v84
	s_waitcnt vmcnt(1)
	ds_write_b32 v70, v85
	s_waitcnt vmcnt(0)
	ds_write_b32 v72, v86
	s_cbranch_scc1 .LBB0_47
; #define LAS __attribute__((address_space(3)))
; __device__ __forceinline__ unsigned pk2(float lo, float hi) { f32x2_t v = {lo, hi}; bf16x2_t b = __builtin_convertvector(v, bf16x2_t); return __builtin_bit_cast(unsigned, b); }
; __device__ __forceinline__ void p0_transpose_item(const float* W, int K, int N, u16* WT, LAS float* scr, int item, int lane, const float* gk = nullptr, const float* bk = nullptr, float* c1 = nullptr, float* c2 = nullptr) {
;     ...
; #pragma unroll
;     for (int j = 0; j < 4; ++j) { const int n = (lane >> 3) + 8 * j; const LAS float* sp = scr + (8 * c) * 33 + n;
;         v4u o; o.x = pk2(sp[0 * 33] * gs[0], sp[1 * 33] * gs[1]); o.y = pk2(sp[2 * 33] * gs[2], sp[3 * 33] * gs[3]); o.z = pk2(sp[4 * 33] * gs[4], sp[5 * 33] * gs[5]); o.w = pk2(sp[6 * 33] * gs[6], sp[7 * 33] * gs[7]);
;         *(v4u*)(WT + (size_t)(n0 + n) * K + k0 + 8 * c) = o; }
;     asm volatile("s_waitcnt lgkmcnt(0)" ::: "memory");
	s_lshl_b32 s12, s3, 3
	s_lshl_b64 s[16:17], s[12:13], 20
	v_readlane_b32 s3, v253, 30
	s_waitcnt lgkmcnt(0)
	s_add_u32 s3, s3, s16
	v_readlane_b32 s12, v253, 31
	ds_read2_b32 v[32:33], v46 offset0:33 offset1:41
	ds_read2_b32 v[34:35], v46 offset1:8
	ds_read2_b32 v[36:37], v46 offset0:66 offset1:74
	ds_read2_b32 v[38:39], v46 offset0:99 offset1:107
	ds_read2_b32 v[40:41], v46 offset0:132 offset1:140
	ds_read2_b32 v[52:53], v46 offset0:165 offset1:173
	ds_read2_b32 v[54:55], v46 offset0:198 offset1:206
	ds_read2_b32 v[56:57], v46 offset0:231 offset1:239
	s_addc_u32 s12, s12, s17
	s_lshl_b32 s14, s14, 1
	s_add_u32 s14, s3, s14
	s_addc_u32 s15, s12, 0
	v_lshlrev_b32_e32 v4, 1, v8
	v_or_b32_e32 v3, s2, v45
	v_lshl_add_u64 v[58:59], s[14:15], 0, v[4:5]
	v_lshlrev_b32_e32 v4, 13, v3
	s_waitcnt lgkmcnt(6)
	v_cvt_pk_bf16_f32 v28, v34, v32
	s_waitcnt lgkmcnt(4)
	v_cvt_pk_bf16_f32 v29, v36, v38
	s_waitcnt lgkmcnt(2)
	v_cvt_pk_bf16_f32 v30, v40, v52
	s_waitcnt lgkmcnt(0)
	v_cvt_pk_bf16_f32 v31, v54, v56
	v_lshl_add_u64 v[60:61], v[58:59], 0, v[4:5]
	global_store_dwordx4 v[60:61], v[28:31], off
	v_or_b32_e32 v3, s2, v47
	v_lshlrev_b32_e32 v4, 13, v3
	v_cvt_pk_bf16_f32 v28, v35, v33
	v_cvt_pk_bf16_f32 v29, v37, v39
	v_cvt_pk_bf16_f32 v30, v41, v53
	v_cvt_pk_bf16_f32 v31, v55, v57
	ds_read2_b32 v[34:35], v46 offset0:49 offset1:57
	ds_read2_b32 v[36:37], v46 offset0:16 offset1:24
	ds_read2_b32 v[38:39], v46 offset0:82 offset1:90
	ds_read2_b32 v[40:41], v46 offset0:115 offset1:123
	ds_read2_b32 v[52:53], v46 offset0:148 offset1:156
	ds_read2_b32 v[54:55], v46 offset0:181 offset1:189
	ds_read2_b32 v[56:57], v46 offset0:214 offset1:222
	ds_read2_b32 v[60:61], v46 offset0:247 offset1:255
	v_or_b32_e32 v3, s2, v48
	v_lshl_add_u64 v[32:33], v[58:59], 0, v[4:5]
	v_lshlrev_b32_e32 v4, 13, v3
	v_or_b32_e32 v3, s2, v49
	global_store_dwordx4 v[32:33], v[28:31], off
	v_lshl_add_u64 v[32:33], v[58:59], 0, v[4:5]
	v_lshlrev_b32_e32 v4, 13, v3
	s_waitcnt lgkmcnt(6)
	v_cvt_pk_bf16_f32 v28, v36, v34
	s_waitcnt lgkmcnt(4)
	v_cvt_pk_bf16_f32 v29, v38, v40
	s_waitcnt lgkmcnt(2)
	v_cvt_pk_bf16_f32 v30, v52, v54
	s_waitcnt lgkmcnt(0)
	v_cvt_pk_bf16_f32 v31, v56, v60
	global_store_dwordx4 v[32:33], v[28:31], off
	v_lshl_add_u64 v[32:33], v[58:59], 0, v[4:5]
	s_nop 0
	v_cvt_pk_bf16_f32 v28, v37, v35
	v_cvt_pk_bf16_f32 v29, v39, v41
	v_cvt_pk_bf16_f32 v30, v53, v55
	v_cvt_pk_bf16_f32 v31, v57, v61
	global_store_dwordx4 v[32:33], v[28:31], off
	s_waitcnt lgkmcnt(0)

; #define LAS __attribute__((address_space(3)))
; __device__ __forceinline__ void p0_transpose_item(const float* W, int K, int N, u16* WT, LAS float* scr, int item, int lane, const float* gk = nullptr, const float* bk = nullptr, float* c1 = nullptr, float* c2 = nullptr) {
;     const int nblk = N / 32, kb = item / nblk, nb = item % nblk, k0 = 64 * kb, n0 = 32 * nb;
; #pragma unroll 8
;     for (int i = 0; i < 32; ++i) { const int kk = 2 * i + (lane >> 5); scr[kk * 33 + (lane & 31)] = W[(size_t)(k0 + kk) * N + n0 + (lane & 31)]; }
;     asm volatile("s_waitcnt lgkmcnt(0)" ::: "memory");
;     const int c = lane & 7;
;     float gs[8];
; #pragma unroll
;     for (int e = 0; e < 8; ++e) gs[e] = gk ? gk[k0 + 8 * c + e] : 1.f;
.LBB0_52:
	s_lshl_b32 s16, s2, 1
	s_lshl_b32 s17, s3, 1
	v_or_b32_e32 v4, s17, v30
	s_add_i32 s31, s16, 4
	s_add_i32 s33, s17, 4
	v_mov_b32_e32 v35, v5
	s_add_i32 s35, s17, 8
	v_lshlrev_b64 v[58:59], 14, v[4:5]
	v_or_b32_e32 v34, s31, v3
	v_or_b32_e32 v4, s33, v30
	v_mov_b32_e32 v33, v5
	v_or_b32_e32 v32, s16, v3
	s_add_i32 s37, s17, 12
	v_lshlrev_b64 v[34:35], 14, v[34:35]
	v_lshlrev_b64 v[60:61], 14, v[4:5]
	v_or_b32_e32 v4, s35, v30
	s_add_i32 s34, s16, 8
	s_add_i32 s36, s16, 12
	s_add_i32 s39, s17, 16
	v_lshlrev_b64 v[32:33], 14, v[32:33]
	v_lshl_add_u64 v[58:59], v[28:29], 0, v[58:59]
	v_lshl_add_u64 v[34:35], v[28:29], 0, v[34:35]
	v_lshlrev_b64 v[62:63], 14, v[4:5]
	v_or_b32_e32 v4, s37, v30
	v_mov_b32_e32 v37, v5
	v_mov_b32_e32 v39, v5
	s_add_i32 s41, s17, 20
	v_or_b32_e32 v36, s34, v3
	v_or_b32_e32 v38, s36, v3
	v_lshl_add_u64 v[32:33], v[28:29], 0, v[32:33]
	v_lshl_add_u64 v[60:61], v[28:29], 0, v[60:61]
	global_load_dword v27, v[58:59], off nt
	global_load_dword v31, v[32:33], off nt
	global_load_dword v74, v[60:61], off nt
	global_load_dword v75, v[34:35], off nt
	v_lshlrev_b64 v[34:35], 14, v[4:5]
	v_or_b32_e32 v4, s39, v30
	s_add_i32 s38, s16, 16
	s_add_i32 s40, s16, 20
	s_add_i32 s43, s17, 24
	v_lshlrev_b64 v[36:37], 14, v[36:37]
	v_lshlrev_b64 v[38:39], 14, v[38:39]
	v_lshl_add_u64 v[32:33], v[28:29], 0, v[62:63]
	v_lshl_add_u64 v[34:35], v[28:29], 0, v[34:35]
	v_lshlrev_b64 v[58:59], 14, v[4:5]
	v_or_b32_e32 v4, s41, v30
	v_mov_b32_e32 v41, v5
	v_mov_b32_e32 v53, v5
	s_add_i32 s42, s16, 24
	s_add_i32 s44, s16, 28
	s_add_i32 s45, s17, 28
	v_or_b32_e32 v40, s38, v3
	v_or_b32_e32 v52, s40, v3
	v_lshl_add_u64 v[36:37], v[28:29], 0, v[36:37]
	v_lshl_add_u64 v[38:39], v[28:29], 0, v[38:39]
	global_load_dword v76, v[32:33], off nt
	global_load_dword v77, v[36:37], off nt
	global_load_dword v78, v[34:35], off nt
	global_load_dword v79, v[38:39], off nt
	v_lshlrev_b64 v[34:35], 14, v[4:5]
	v_or_b32_e32 v4, s43, v30
	v_mov_b32_e32 v55, v5
	v_mov_b32_e32 v57, v5
	v_or_b32_e32 v54, s42, v3
	v_or_b32_e32 v56, s44, v3
	v_lshlrev_b64 v[40:41], 14, v[40:41]
	v_lshlrev_b64 v[52:53], 14, v[52:53]
	v_lshl_add_u64 v[32:33], v[28:29], 0, v[58:59]
	v_lshl_add_u64 v[34:35], v[28:29], 0, v[34:35]
	v_lshlrev_b64 v[36:37], 14, v[4:5]
	v_or_b32_e32 v4, s45, v30
	v_lshlrev_b64 v[54:55], 14, v[54:55]
	v_lshlrev_b64 v[56:57], 14, v[56:57]
	v_lshl_add_u64 v[40:41], v[28:29], 0, v[40:41]
	v_lshl_add_u64 v[52:53], v[28:29], 0, v[52:53]
	global_load_dword v80, v[32:33], off nt
	global_load_dword v81, v[40:41], off nt
	global_load_dword v82, v[34:35], off nt
	global_load_dword v83, v[52:53], off nt
	v_lshl_add_u64 v[32:33], v[28:29], 0, v[36:37]
	v_lshlrev_b64 v[34:35], 14, v[4:5]
	v_lshl_add_u64 v[54:55], v[28:29], 0, v[54:55]
	v_lshl_add_u64 v[56:57], v[28:29], 0, v[56:57]
	v_lshl_add_u64 v[34:35], v[28:29], 0, v[34:35]
	global_load_dword v4, v[32:33], off nt
	global_load_dword v84, v[54:55], off nt
	global_load_dword v85, v[34:35], off nt
	global_load_dword v86, v[56:57], off nt
	v_or_b32_e32 v34, s16, v1
	v_or_b32_e32 v32, s17, v2
	s_add_i32 s3, s3, 16
	s_add_i32 s2, s2, 16
	s_add_i32 s12, s12, -16
	v_mad_u64_u32 v[32:33], s[16:17], v32, s26, v[6:7]
	v_mad_u64_u32 v[34:35], s[16:17], v34, s26, v[6:7]
	v_or_b32_e32 v33, s31, v1
	v_or_b32_e32 v35, s33, v2
	v_or_b32_e32 v52, s34, v1
	v_or_b32_e32 v40, s35, v2
	v_or_b32_e32 v56, s36, v1
	v_or_b32_e32 v54, s37, v2
	v_or_b32_e32 v60, s38, v1
	v_or_b32_e32 v58, s39, v2
	v_or_b32_e32 v64, s40, v1
	v_or_b32_e32 v62, s41, v2
	v_or_b32_e32 v68, s42, v1
	v_or_b32_e32 v66, s43, v2
	v_or_b32_e32 v72, s44, v1
	v_or_b32_e32 v70, s45, v2
	s_cmp_lg_u32 s12, 0
	v_mad_u64_u32 v[36:37], s[16:17], v35, s26, v[6:7]
	v_mad_u64_u32 v[38:39], s[16:17], v33, s26, v[6:7]
	v_mad_u64_u32 v[40:41], s[16:17], v40, s26, v[6:7]
	v_mad_u64_u32 v[52:53], s[16:17], v52, s26, v[6:7]
	v_mad_u64_u32 v[54:55], s[16:17], v54, s26, v[6:7]
	v_mad_u64_u32 v[56:57], s[16:17], v56, s26, v[6:7]
	v_mad_u64_u32 v[58:59], s[16:17], v58, s26, v[6:7]
	v_mad_u64_u32 v[60:61], s[16:17], v60, s26, v[6:7]
	v_mad_u64_u32 v[62:63], s[16:17], v62, s26, v[6:7]
	v_mad_u64_u32 v[64:65], s[16:17], v64, s26, v[6:7]
	v_mad_u64_u32 v[66:67], s[16:17], v66, s26, v[6:7]
	v_mad_u64_u32 v[68:69], s[16:17], v68, s26, v[6:7]
	v_mad_u64_u32 v[70:71], s[16:17], v70, s26, v[6:7]
	v_mad_u64_u32 v[72:73], s[16:17], v72, s26, v[6:7]
	s_waitcnt vmcnt(15)
	ds_write_b32 v32, v27
	s_waitcnt vmcnt(14)
	ds_write_b32 v34, v31
	s_waitcnt vmcnt(13)
	ds_write_b32 v36, v74
	s_waitcnt vmcnt(12)
	ds_write_b32 v38, v75
	s_waitcnt vmcnt(11)
	ds_write_b32 v40, v76
	s_waitcnt vmcnt(10)
	ds_write_b32 v52, v77
	s_waitcnt vmcnt(9)
	ds_write_b32 v54, v78
	s_waitcnt vmcnt(8)
	ds_write_b32 v56, v79
	s_waitcnt vmcnt(7)
	ds_write_b32 v58, v80
	s_waitcnt vmcnt(6)
	ds_write_b32 v60, v81
	s_waitcnt vmcnt(5)
	ds_write_b32 v62, v82
	s_waitcnt vmcnt(4)
	ds_write_b32 v64, v83
	s_waitcnt vmcnt(3)
	ds_write_b32 v66, v4
	s_waitcnt vmcnt(2)
	ds_write_b32 v68, v84
	s_waitcnt vmcnt(1)
	ds_write_b32 v70, v85
	s_waitcnt vmcnt(0)
	ds_write_b32 v72, v86
	s_cbranch_scc1 .LBB0_52
	s_lshl_b32 s12, s14, 10
	v_readlane_b32 s36, v253, 9
	s_lshl_b64 s[2:3], s[12:13], 2
	v_readlane_b32 s40, v253, 13
	s_waitcnt lgkmcnt(0)
	v_readlane_b32 s41, v253, 14
	s_add_u32 s16, s40, s2
	v_or_b32_e32 v3, s30, v8
	v_cndmask_b32_e64 v4, 0, 1, s[10:11]
	s_addc_u32 s17, s41, s3
	v_mov_b32_e32 v29, 1.0
	v_cmp_ne_u32_e64 s[2:3], 1, v4
	s_andn2_b64 vcc, exec, s[10:11]
	v_lshlrev_b32_e32 v3, 2, v3
	v_mov_b32_e32 v28, 1.0
	v_readlane_b32 s37, v253, 10
	v_readlane_b32 s38, v253, 11
	v_readlane_b32 s39, v253, 12
	v_readlane_b32 s42, v253, 15
	v_readlane_b32 s43, v253, 16
	v_readlane_b32 s44, v253, 17
	v_readlane_b32 s45, v253, 18
	v_readlane_b32 s46, v253, 19
	v_readlane_b32 s47, v253, 20
	v_readlane_b32 s48, v253, 21
	v_readlane_b32 s49, v253, 22
	v_readlane_b32 s50, v253, 23
	v_readlane_b32 s51, v253, 24
	s_cbranch_vccnz .LBB0_55
	global_load_dword v28, v3, s[16:17] nt

; __device__ __forceinline__ float shx(float v, int m, int lane) { return __builtin_bit_cast(float, __builtin_amdgcn_ds_bpermute((lane ^ m) << 2, __builtin_bit_cast(int, v))); }
; __device__ __forceinline__ float shx(float v, int m, int lane) { return __builtin_bit_cast(float, __builtin_amdgcn_ds_bpermute((lane ^ m) << 2, __builtin_bit_cast(int, v))); }
; __device__ __forceinline__ void p0_transpose_item(const float* W, int K, int N, u16* WT, LAS float* scr, int item, int lane, const float* gk = nullptr, const float* bk = nullptr, float* c1 = nullptr, float* c2 = nullptr) {
;     ...
;     if (gk) {
;         const int n = lane & 31, kh = (lane >> 5) * 32; float s1 = 0.f, s2 = 0.f;
; #pragma unroll 8
;         for (int kk = 0; kk < 32; ++kk) { const float wv = scr[(kh + kk) * 33 + n]; s1 += gk[k0 + kh + kk] * wv; s2 += bk[k0 + kh + kk] * wv; }
;         s1 += shx(s1, 32, lane); s2 += shx(s2, 32, lane);
;         if (lane < 32) { atomicAdd(c1 + n0 + n, s1); atomicAdd(c2 + n0 + n, s2); }
;     }
.LBB0_71:
	v_lshl_add_u64 v[60:61], v[38:39], 0, s[2:3]
	v_lshl_add_u64 v[64:65], v[40:41], 0, s[2:3]
	global_load_dwordx4 v[52:55], v[60:61], off nt
	global_load_dwordx4 v[56:59], v[64:65], off nt
	s_nop 0
	global_load_dwordx4 v[60:63], v[60:61], off offset:16 nt
	s_nop 0
	global_load_dwordx4 v[64:67], v[64:65], off offset:16 nt
	ds_read2_b32 v[68:69], v3 offset1:33
	ds_read2_b32 v[70:71], v3 offset0:66 offset1:99
	ds_read2_b32 v[72:73], v3 offset0:132 offset1:165
	ds_read2_b32 v[74:75], v3 offset0:198 offset1:231
	s_add_u32 s2, s2, 32
	s_waitcnt lgkmcnt(3)
	v_mov_b32_e32 v4, v69
	s_waitcnt lgkmcnt(2)
	v_mov_b32_e32 v76, v71
	s_waitcnt lgkmcnt(1)
	v_mov_b32_e32 v78, v73
	s_addc_u32 s3, s3, 0
	s_waitcnt lgkmcnt(0)
	v_mov_b32_e32 v80, v75
	v_add_u32_e32 v3, 0x420, v3
	s_cmpk_eq_i32 s2, 0x80
	s_waitcnt vmcnt(3)
	v_mov_b32_e32 v82, v52
	s_waitcnt vmcnt(2)
	v_mov_b32_e32 v83, v56
	v_mov_b32_e32 v56, v53
	v_pk_fma_f32 v[36:37], v[68:69], v[82:83], v[36:37] op_sel_hi:[0,1,1]
	v_mov_b32_e32 v52, v54
	v_mov_b32_e32 v53, v58
	v_pk_fma_f32 v[36:37], v[4:5], v[56:57], v[36:37] op_sel_hi:[0,1,1]
	v_mov_b32_e32 v58, v55
	v_pk_fma_f32 v[36:37], v[70:71], v[52:53], v[36:37] op_sel_hi:[0,1,1]
	s_waitcnt vmcnt(1)
	v_mov_b32_e32 v54, v60
	s_waitcnt vmcnt(0)
	v_mov_b32_e32 v55, v64
	v_pk_fma_f32 v[36:37], v[76:77], v[58:59], v[36:37] op_sel_hi:[0,1,1]
	v_mov_b32_e32 v64, v61
	v_pk_fma_f32 v[36:37], v[72:73], v[54:55], v[36:37] op_sel_hi:[0,1,1]
	v_mov_b32_e32 v60, v62
	v_mov_b32_e32 v61, v66
	v_pk_fma_f32 v[36:37], v[78:79], v[64:65], v[36:37] op_sel_hi:[0,1,1]
	v_mov_b32_e32 v66, v63
	v_pk_fma_f32 v[36:37], v[74:75], v[60:61], v[36:37] op_sel_hi:[0,1,1]
	v_pk_fma_f32 v[36:37], v[80:81], v[66:67], v[36:37] op_sel_hi:[0,1,1]
	s_cbranch_scc0 .LBB0_71
	ds_bpermute_b32 v3, v9, v36
	ds_bpermute_b32 v4, v9, v37
	s_and_saveexec_b64 s[2:3], s[0:1]
	s_cbranch_execz .LBB0_74
	s_mul_i32 s12, s14, 0x2800
	s_lshl_b64 s[16:17], s[12:13], 2
	s_add_u32 s12, s62, s16
	s_addc_u32 s17, s63, s17
	s_lshl_b32 s16, s15, 2
	s_add_u32 s16, s12, s16
	v_mov_b32_e32 v27, v5
	s_addc_u32 s17, s17, 0
	v_lshl_add_u64 v[38:39], s[16:17], 0, v[26:27]
	s_waitcnt lgkmcnt(1)
	v_add_f32_e32 v3, v36, v3
	v_add_co_u32_e32 v36, vcc, 0x4000, v38
	s_waitcnt lgkmcnt(0)
	v_add_f32_e32 v4, v37, v4
	global_atomic_add_f32 v26, v3, s[16:17]
	v_addc_co_u32_e32 v37, vcc, 0, v39, vcc
	global_atomic_add_f32 v[36:37], v4, off

; #define LAS __attribute__((address_space(3)))
; __device__ __forceinline__ void p0_transpose_item(const float* W, int K, int N, u16* WT, LAS float* scr, int item, int lane, const float* gk = nullptr, const float* bk = nullptr, float* c1 = nullptr, float* c2 = nullptr) {
;     const int nblk = N / 32, kb = item / nblk, nb = item % nblk, k0 = 64 * kb, n0 = 32 * nb;
; #pragma unroll 8
;     for (int i = 0; i < 32; ++i) { const int kk = 2 * i + (lane >> 5); scr[kk * 33 + (lane & 31)] = W[(size_t)(k0 + kk) * N + n0 + (lane & 31)]; }
;     asm volatile("s_waitcnt lgkmcnt(0)" ::: "memory");
.LBB0_79:
	s_lshl_b32 s16, s3, 1
	s_lshl_b32 s17, s12, 1
	v_or_b32_e32 v4, s17, v30
	s_add_i32 s30, s16, 4
	s_add_i32 s31, s17, 4
	v_mov_b32_e32 v35, v5
	s_add_i32 s34, s17, 8
	v_lshlrev_b64 v[58:59], 12, v[4:5]
	v_or_b32_e32 v34, s30, v3
	v_or_b32_e32 v4, s31, v30
	v_mov_b32_e32 v33, v5
	v_or_b32_e32 v32, s16, v3
	s_add_i32 s36, s17, 12
	v_lshlrev_b64 v[34:35], 12, v[34:35]
	v_lshlrev_b64 v[60:61], 12, v[4:5]
	v_or_b32_e32 v4, s34, v30
	s_add_i32 s33, s16, 8
	s_add_i32 s35, s16, 12
	s_add_i32 s38, s17, 16
	v_lshlrev_b64 v[32:33], 12, v[32:33]
	v_lshl_add_u64 v[58:59], v[28:29], 0, v[58:59]
	v_lshl_add_u64 v[34:35], v[28:29], 0, v[34:35]
	v_lshlrev_b64 v[62:63], 12, v[4:5]
	v_or_b32_e32 v4, s36, v30
	v_mov_b32_e32 v37, v5
	v_mov_b32_e32 v39, v5
	s_add_i32 s40, s17, 20
	v_or_b32_e32 v36, s33, v3
	v_or_b32_e32 v38, s35, v3
	v_lshl_add_u64 v[32:33], v[28:29], 0, v[32:33]
	v_lshl_add_u64 v[60:61], v[28:29], 0, v[60:61]
	global_load_dword v27, v[58:59], off nt
	global_load_dword v31, v[32:33], off nt
	global_load_dword v74, v[60:61], off nt
	global_load_dword v75, v[34:35], off nt
	v_lshlrev_b64 v[34:35], 12, v[4:5]
	v_or_b32_e32 v4, s38, v30
	s_add_i32 s37, s16, 16
	s_add_i32 s39, s16, 20
	s_add_i32 s42, s17, 24
	v_lshlrev_b64 v[36:37], 12, v[36:37]
	v_lshlrev_b64 v[38:39], 12, v[38:39]
	v_lshl_add_u64 v[32:33], v[28:29], 0, v[62:63]
	v_lshl_add_u64 v[34:35], v[28:29], 0, v[34:35]
	v_lshlrev_b64 v[58:59], 12, v[4:5]
	v_or_b32_e32 v4, s40, v30
	v_mov_b32_e32 v41, v5
	v_mov_b32_e32 v53, v5
	s_add_i32 s41, s16, 24
	s_add_i32 s43, s16, 28
	s_add_i32 s44, s17, 28
	v_or_b32_e32 v40, s37, v3
	v_or_b32_e32 v52, s39, v3
	v_lshl_add_u64 v[36:37], v[28:29], 0, v[36:37]
	v_lshl_add_u64 v[38:39], v[28:29], 0, v[38:39]
	global_load_dword v76, v[32:33], off nt
	global_load_dword v77, v[36:37], off nt
	global_load_dword v78, v[34:35], off nt
	global_load_dword v79, v[38:39], off nt
	v_lshlrev_b64 v[34:35], 12, v[4:5]
	v_or_b32_e32 v4, s42, v30
	v_mov_b32_e32 v55, v5
	v_mov_b32_e32 v57, v5
	v_or_b32_e32 v54, s41, v3
	v_or_b32_e32 v56, s43, v3
	v_lshlrev_b64 v[40:41], 12, v[40:41]
	v_lshlrev_b64 v[52:53], 12, v[52:53]
	v_lshl_add_u64 v[32:33], v[28:29], 0, v[58:59]
	v_lshl_add_u64 v[34:35], v[28:29], 0, v[34:35]
	v_lshlrev_b64 v[36:37], 12, v[4:5]
	v_or_b32_e32 v4, s44, v30
	v_lshlrev_b64 v[54:55], 12, v[54:55]
	v_lshlrev_b64 v[56:57], 12, v[56:57]
	v_lshl_add_u64 v[40:41], v[28:29], 0, v[40:41]
	v_lshl_add_u64 v[52:53], v[28:29], 0, v[52:53]
	global_load_dword v80, v[32:33], off nt
	global_load_dword v81, v[40:41], off nt
	global_load_dword v82, v[34:35], off nt
	global_load_dword v83, v[52:53], off nt
	v_lshl_add_u64 v[32:33], v[28:29], 0, v[36:37]
	v_lshlrev_b64 v[34:35], 12, v[4:5]
	v_lshl_add_u64 v[54:55], v[28:29], 0, v[54:55]
	v_lshl_add_u64 v[56:57], v[28:29], 0, v[56:57]
	v_lshl_add_u64 v[34:35], v[28:29], 0, v[34:35]
	global_load_dword v4, v[32:33], off nt
	global_load_dword v84, v[54:55], off nt
	global_load_dword v85, v[34:35], off nt
	global_load_dword v86, v[56:57], off nt
	v_or_b32_e32 v34, s16, v1
	v_or_b32_e32 v32, s17, v2
	s_add_i32 s12, s12, 16
	s_add_i32 s3, s3, 16
	s_add_i32 s15, s15, -16
	v_mad_u64_u32 v[32:33], s[16:17], v32, s26, v[6:7]
	v_mad_u64_u32 v[34:35], s[16:17], v34, s26, v[6:7]
	v_or_b32_e32 v33, s30, v1
	v_or_b32_e32 v35, s31, v2
	v_or_b32_e32 v52, s33, v1
	v_or_b32_e32 v40, s34, v2
	v_or_b32_e32 v56, s35, v1
	v_or_b32_e32 v54, s36, v2
	v_or_b32_e32 v60, s37, v1
	v_or_b32_e32 v58, s38, v2
	v_or_b32_e32 v64, s39, v1
	v_or_b32_e32 v62, s40, v2
	v_or_b32_e32 v68, s41, v1
	v_or_b32_e32 v66, s42, v2
	v_or_b32_e32 v72, s43, v1
	v_or_b32_e32 v70, s44, v2
	s_cmp_lg_u32 s15, 0
	v_mad_u64_u32 v[36:37], s[16:17], v35, s26, v[6:7]
	v_mad_u64_u32 v[38:39], s[16:17], v33, s26, v[6:7]
	v_mad_u64_u32 v[40:41], s[16:17], v40, s26, v[6:7]
	v_mad_u64_u32 v[52:53], s[16:17], v52, s26, v[6:7]
	v_mad_u64_u32 v[54:55], s[16:17], v54, s26, v[6:7]
	v_mad_u64_u32 v[56:57], s[16:17], v56, s26, v[6:7]
	v_mad_u64_u32 v[58:59], s[16:17], v58, s26, v[6:7]
	v_mad_u64_u32 v[60:61], s[16:17], v60, s26, v[6:7]
	v_mad_u64_u32 v[62:63], s[16:17], v62, s26, v[6:7]
	v_mad_u64_u32 v[64:65], s[16:17], v64, s26, v[6:7]
	v_mad_u64_u32 v[66:67], s[16:17], v66, s26, v[6:7]
	v_mad_u64_u32 v[68:69], s[16:17], v68, s26, v[6:7]
	v_mad_u64_u32 v[70:71], s[16:17], v70, s26, v[6:7]
	v_mad_u64_u32 v[72:73], s[16:17], v72, s26, v[6:7]
	s_waitcnt vmcnt(15)
	ds_write_b32 v32, v27
	s_waitcnt vmcnt(14)
	ds_write_b32 v34, v31
	s_waitcnt vmcnt(13)
	ds_write_b32 v36, v74
	s_waitcnt vmcnt(12)
	ds_write_b32 v38, v75
	s_waitcnt vmcnt(11)
	ds_write_b32 v40, v76
	s_waitcnt vmcnt(10)
	ds_write_b32 v52, v77
	s_waitcnt vmcnt(9)
	ds_write_b32 v54, v78
	s_waitcnt vmcnt(8)
	ds_write_b32 v56, v79
	s_waitcnt vmcnt(7)
	ds_write_b32 v58, v80
	s_waitcnt vmcnt(6)
	ds_write_b32 v60, v81
	s_waitcnt vmcnt(5)
	ds_write_b32 v62, v82
	s_waitcnt vmcnt(4)
	ds_write_b32 v64, v83
	s_waitcnt vmcnt(3)
	ds_write_b32 v66, v4
	s_waitcnt vmcnt(2)
	ds_write_b32 v68, v84
	s_waitcnt vmcnt(1)
	ds_write_b32 v70, v85
	s_waitcnt vmcnt(0)
	ds_write_b32 v72, v86
	s_cbranch_scc1 .LBB0_79
; #define LAS __attribute__((address_space(3)))
; __device__ __forceinline__ unsigned pk2(float lo, float hi) { f32x2_t v = {lo, hi}; bf16x2_t b = __builtin_convertvector(v, bf16x2_t); return __builtin_bit_cast(unsigned, b); }
; __device__ __forceinline__ void p0_transpose_item(const float* W, int K, int N, u16* WT, LAS float* scr, int item, int lane, const float* gk = nullptr, const float* bk = nullptr, float* c1 = nullptr, float* c2 = nullptr) {
;     ...
; #pragma unroll
;     for (int j = 0; j < 4; ++j) { const int n = (lane >> 3) + 8 * j; const LAS float* sp = scr + (8 * c) * 33 + n;
;         v4u o; o.x = pk2(sp[0 * 33] * gs[0], sp[1 * 33] * gs[1]); o.y = pk2(sp[2 * 33] * gs[2], sp[3 * 33] * gs[3]); o.z = pk2(sp[4 * 33] * gs[4], sp[5 * 33] * gs[5]); o.w = pk2(sp[6 * 33] * gs[6], sp[7 * 33] * gs[7]);
;         *(v4u*)(WT + (size_t)(n0 + n) * K + k0 + 8 * c) = o; }
;     asm volatile("s_waitcnt lgkmcnt(0)" ::: "memory");
	s_waitcnt lgkmcnt(0)
	ds_read2_b32 v[32:33], v46 offset0:33 offset1:41
	ds_read2_b32 v[34:35], v46 offset1:8
	ds_read2_b32 v[36:37], v46 offset0:66 offset1:74
	ds_read2_b32 v[38:39], v46 offset0:99 offset1:107
	ds_read2_b32 v[40:41], v46 offset0:132 offset1:140
	ds_read2_b32 v[52:53], v46 offset0:165 offset1:173
	ds_read2_b32 v[54:55], v46 offset0:198 offset1:206
	ds_read2_b32 v[56:57], v46 offset0:231 offset1:239
	s_lshl_b32 s12, s14, 1
	v_or_b32_e32 v3, s2, v45
	v_lshl_add_u64 v[58:59], v[10:11], 0, s[12:13]
	v_lshlrev_b32_e32 v4, 11, v3
	s_waitcnt lgkmcnt(6)
	v_cvt_pk_bf16_f32 v28, v34, v32
	s_waitcnt lgkmcnt(4)
	v_cvt_pk_bf16_f32 v29, v36, v38
	s_waitcnt lgkmcnt(2)
	v_cvt_pk_bf16_f32 v30, v40, v52
	s_waitcnt lgkmcnt(0)
	v_cvt_pk_bf16_f32 v31, v54, v56
	v_lshl_add_u64 v[60:61], v[58:59], 0, v[4:5]
	global_store_dwordx4 v[60:61], v[28:31], off
	v_or_b32_e32 v3, s2, v47
	v_lshlrev_b32_e32 v4, 11, v3
	v_cvt_pk_bf16_f32 v28, v35, v33
	v_cvt_pk_bf16_f32 v29, v37, v39
	v_cvt_pk_bf16_f32 v30, v41, v53
	v_cvt_pk_bf16_f32 v31, v55, v57
	ds_read2_b32 v[34:35], v46 offset0:49 offset1:57
	ds_read2_b32 v[36:37], v46 offset0:16 offset1:24
	ds_read2_b32 v[38:39], v46 offset0:82 offset1:90
	ds_read2_b32 v[40:41], v46 offset0:115 offset1:123
	ds_read2_b32 v[52:53], v46 offset0:148 offset1:156
	ds_read2_b32 v[54:55], v46 offset0:181 offset1:189
	ds_read2_b32 v[56:57], v46 offset0:214 offset1:222
	ds_read2_b32 v[60:61], v46 offset0:247 offset1:255
	v_or_b32_e32 v3, s2, v48
	v_lshl_add_u64 v[32:33], v[58:59], 0, v[4:5]
	v_lshlrev_b32_e32 v4, 11, v3
	v_or_b32_e32 v3, s2, v49
	global_store_dwordx4 v[32:33], v[28:31], off
	v_lshl_add_u64 v[32:33], v[58:59], 0, v[4:5]
	v_lshlrev_b32_e32 v4, 11, v3
	s_waitcnt lgkmcnt(6)
	v_cvt_pk_bf16_f32 v28, v36, v34
	s_waitcnt lgkmcnt(4)
	v_cvt_pk_bf16_f32 v29, v38, v40
	s_waitcnt lgkmcnt(2)
	v_cvt_pk_bf16_f32 v30, v52, v54
	s_waitcnt lgkmcnt(0)
	v_cvt_pk_bf16_f32 v31, v56, v60
	global_store_dwordx4 v[32:33], v[28:31], off
	v_lshl_add_u64 v[32:33], v[58:59], 0, v[4:5]
	s_nop 0
	v_cvt_pk_bf16_f32 v28, v37, v35
	v_cvt_pk_bf16_f32 v29, v39, v41
	v_cvt_pk_bf16_f32 v30, v53, v55
	v_cvt_pk_bf16_f32 v31, v57, v61
	global_store_dwordx4 v[32:33], v[28:31], off
	s_waitcnt lgkmcnt(0)

; __device__ __forceinline__ float shx(float v, int m, int lane) { return __builtin_bit_cast(float, __builtin_amdgcn_ds_bpermute((lane ^ m) << 2, __builtin_bit_cast(int, v))); }
; #define LAS __attribute__((address_space(3)))
; __device__ __forceinline__ unsigned pk2(float lo, float hi) { f32x2_t v = {lo, hi}; bf16x2_t b = __builtin_convertvector(v, bf16x2_t); return __builtin_bit_cast(unsigned, b); }
; __device__ __forceinline__ float shx(float v, int m, int lane) { return __builtin_bit_cast(float, __builtin_amdgcn_ds_bpermute((lane ^ m) << 2, __builtin_bit_cast(int, v))); }
; __device__ __forceinline__ void p0_transpose_item(const float* W, int K, int N, u16* WT, LAS float* scr, int item, int lane, const float* gk = nullptr, const float* bk = nullptr, float* c1 = nullptr, float* c2 = nullptr) {
;     const int nblk = N / 32, kb = item / nblk, nb = item % nblk, k0 = 64 * kb, n0 = 32 * nb;
; #pragma unroll 8
;     for (int i = 0; i < 32; ++i) { const int kk = 2 * i + (lane >> 5); scr[kk * 33 + (lane & 31)] = W[(size_t)(k0 + kk) * N + n0 + (lane & 31)]; }
;     asm volatile("s_waitcnt lgkmcnt(0)" ::: "memory");
;     const int c = lane & 7;
;     float gs[8];
; #pragma unroll
;     for (int e = 0; e < 8; ++e) gs[e] = gk ? gk[k0 + 8 * c + e] : 1.f;
;     if (gk) {
;         const int n = lane & 31, kh = (lane >> 5) * 32; float s1 = 0.f, s2 = 0.f;
; #pragma unroll 8
;         for (int kk = 0; kk < 32; ++kk) { const float wv = scr[(kh + kk) * 33 + n]; s1 += gk[k0 + kh + kk] * wv; s2 += bk[k0 + kh + kk] * wv; }
;         s1 += shx(s1, 32, lane); s2 += shx(s2, 32, lane);
;         if (lane < 32) { atomicAdd(c1 + n0 + n, s1); atomicAdd(c2 + n0 + n, s2); }
;     }
; #pragma unroll
;     for (int j = 0; j < 4; ++j) { const int n = (lane >> 3) + 8 * j; const LAS float* sp = scr + (8 * c) * 33 + n;
;         v4u o; o.x = pk2(sp[0 * 33] * gs[0], sp[1 * 33] * gs[1]); o.y = pk2(sp[2 * 33] * gs[2], sp[3 * 33] * gs[3]); o.z = pk2(sp[4 * 33] * gs[4], sp[5 * 33] * gs[5]); o.w = pk2(sp[6 * 33] * gs[6], sp[7 * 33] * gs[7]);
;         *(v4u*)(WT + (size_t)(n0 + n) * K + k0 + 8 * c) = o; }
;     asm volatile("s_waitcnt lgkmcnt(0)" ::: "memory");
.LBB0_84:
	s_lshl_b32 s30, s12, 1
	s_lshl_b32 s31, s14, 1
	v_or_b32_e32 v27, s30, v3
	v_or_b32_e32 v30, s31, v4
	s_add_i32 s33, s30, 4
	s_add_i32 s34, s31, 4
	s_add_i32 s35, s30, 8
	s_add_i32 s36, s31, 8
	s_add_i32 s37, s30, 12
	s_add_i32 s38, s31, 12
	s_add_i32 s39, s30, 16
	s_add_i32 s40, s31, 16
	s_add_i32 s41, s30, 20
	s_add_i32 s42, s31, 20
	s_add_i32 s43, s30, 24
	s_add_i32 s44, s31, 24
	s_add_i32 s45, s30, 28
	s_add_i32 s46, s31, 28
	v_mad_u64_u32 v[30:31], s[16:17], v30, s27, v[28:29]
	v_mad_u64_u32 v[32:33], s[16:17], v27, s27, v[28:29]
	v_or_b32_e32 v27, s33, v3
	v_or_b32_e32 v34, s34, v4
	v_or_b32_e32 v40, s35, v3
	v_or_b32_e32 v38, s36, v4
	v_or_b32_e32 v54, s37, v3
	v_or_b32_e32 v52, s38, v4
	v_or_b32_e32 v58, s39, v3
	v_or_b32_e32 v56, s40, v4
	v_or_b32_e32 v62, s41, v3
	v_or_b32_e32 v60, s42, v4
	v_or_b32_e32 v66, s43, v3
	v_or_b32_e32 v64, s44, v4
	v_or_b32_e32 v70, s45, v3
	v_or_b32_e32 v68, s46, v4
	v_mad_u64_u32 v[34:35], s[16:17], v34, s27, v[28:29]
	v_mad_u64_u32 v[36:37], s[16:17], v27, s27, v[28:29]
	v_mad_u64_u32 v[38:39], s[16:17], v38, s27, v[28:29]
	v_mad_u64_u32 v[40:41], s[16:17], v40, s27, v[28:29]
	v_mad_u64_u32 v[52:53], s[16:17], v52, s27, v[28:29]
	v_mad_u64_u32 v[54:55], s[16:17], v54, s27, v[28:29]
	v_mad_u64_u32 v[56:57], s[16:17], v56, s27, v[28:29]
	v_mad_u64_u32 v[58:59], s[16:17], v58, s27, v[28:29]
	v_mad_u64_u32 v[60:61], s[16:17], v60, s27, v[28:29]
	v_mad_u64_u32 v[62:63], s[16:17], v62, s27, v[28:29]
	v_mad_u64_u32 v[64:65], s[16:17], v64, s27, v[28:29]
	v_mad_u64_u32 v[66:67], s[16:17], v66, s27, v[28:29]
	v_mad_u64_u32 v[68:69], s[16:17], v68, s27, v[28:29]
	v_mad_u64_u32 v[70:71], s[16:17], v70, s27, v[28:29]
	global_load_dword v27, v[30:31], off nt
	global_load_dword v72, v[32:33], off nt
	global_load_dword v73, v[34:35], off nt
	global_load_dword v74, v[36:37], off nt
	global_load_dword v75, v[38:39], off nt
	global_load_dword v76, v[40:41], off nt
	global_load_dword v77, v[52:53], off nt
	global_load_dword v78, v[54:55], off nt
	global_load_dword v79, v[56:57], off nt
	global_load_dword v80, v[58:59], off nt
	global_load_dword v81, v[60:61], off nt
	global_load_dword v82, v[62:63], off nt
	global_load_dword v83, v[64:65], off nt
	global_load_dword v84, v[66:67], off nt
	global_load_dword v85, v[68:69], off nt
	global_load_dword v86, v[70:71], off nt
	v_or_b32_e32 v32, s30, v1
	v_or_b32_e32 v30, s31, v2
	s_add_i32 s14, s14, 16
	s_add_i32 s12, s12, 16
	s_add_i32 s15, s15, -16
	v_mad_u64_u32 v[30:31], s[16:17], v30, s26, v[6:7]
	v_mad_u64_u32 v[32:33], s[16:17], v32, s26, v[6:7]
	v_or_b32_e32 v31, s33, v1
	v_or_b32_e32 v33, s34, v2
	v_or_b32_e32 v40, s35, v1
	v_or_b32_e32 v38, s36, v2
	v_or_b32_e32 v54, s37, v1
	v_or_b32_e32 v52, s38, v2
	v_or_b32_e32 v58, s39, v1
	v_or_b32_e32 v56, s40, v2
	v_or_b32_e32 v62, s41, v1
	v_or_b32_e32 v60, s42, v2
	v_or_b32_e32 v66, s43, v1
	v_or_b32_e32 v64, s44, v2
	v_or_b32_e32 v70, s45, v1
	v_or_b32_e32 v68, s46, v2
	s_cmp_lg_u32 s15, 0
	v_mad_u64_u32 v[34:35], s[16:17], v33, s26, v[6:7]
	v_mad_u64_u32 v[36:37], s[16:17], v31, s26, v[6:7]
	v_mad_u64_u32 v[38:39], s[16:17], v38, s26, v[6:7]
	v_mad_u64_u32 v[40:41], s[16:17], v40, s26, v[6:7]
	v_mad_u64_u32 v[52:53], s[16:17], v52, s26, v[6:7]
	v_mad_u64_u32 v[54:55], s[16:17], v54, s26, v[6:7]
	v_mad_u64_u32 v[56:57], s[16:17], v56, s26, v[6:7]
	v_mad_u64_u32 v[58:59], s[16:17], v58, s26, v[6:7]
	v_mad_u64_u32 v[60:61], s[16:17], v60, s26, v[6:7]
	v_mad_u64_u32 v[62:63], s[16:17], v62, s26, v[6:7]
	v_mad_u64_u32 v[64:65], s[16:17], v64, s26, v[6:7]
	v_mad_u64_u32 v[66:67], s[16:17], v66, s26, v[6:7]
	v_mad_u64_u32 v[68:69], s[16:17], v68, s26, v[6:7]
	v_mad_u64_u32 v[70:71], s[16:17], v70, s26, v[6:7]
	s_waitcnt vmcnt(15)
	ds_write_b32 v30, v27
	s_waitcnt vmcnt(14)
	ds_write_b32 v32, v72
	s_waitcnt vmcnt(13)
	ds_write_b32 v34, v73
	s_waitcnt vmcnt(12)
	ds_write_b32 v36, v74
	s_waitcnt vmcnt(11)
	ds_write_b32 v38, v75
	s_waitcnt vmcnt(10)
	ds_write_b32 v40, v76
	s_waitcnt vmcnt(9)
	ds_write_b32 v52, v77
	s_waitcnt vmcnt(8)
	ds_write_b32 v54, v78
	s_waitcnt vmcnt(7)
	ds_write_b32 v56, v79
	s_waitcnt vmcnt(6)
	ds_write_b32 v58, v80
	s_waitcnt vmcnt(5)
	ds_write_b32 v60, v81
	s_waitcnt vmcnt(4)
	ds_write_b32 v62, v82
	s_waitcnt vmcnt(3)
	ds_write_b32 v64, v83
	s_waitcnt vmcnt(2)
	ds_write_b32 v66, v84
	s_waitcnt vmcnt(1)
	ds_write_b32 v68, v85
	s_waitcnt vmcnt(0)
	ds_write_b32 v70, v86
	s_cbranch_scc1 .LBB0_84
	s_waitcnt lgkmcnt(0)
	ds_read2_b32 v[32:33], v46 offset0:33 offset1:41
	ds_read2_b32 v[34:35], v46 offset1:8
	ds_read2_b32 v[36:37], v46 offset0:66 offset1:74
	ds_read2_b32 v[38:39], v46 offset0:99 offset1:107
	ds_read2_b32 v[40:41], v46 offset0:132 offset1:140
	ds_read2_b32 v[52:53], v46 offset0:165 offset1:173
	ds_read2_b32 v[54:55], v46 offset0:198 offset1:206
	ds_read2_b32 v[56:57], v46 offset0:231 offset1:239
	s_and_b32 s3, 0xffff, s3
	s_and_b32 s2, 0xffff, s2
	s_lshl_b32 s12, s2, 1
	v_or_b32_e32 v3, s3, v45
	v_lshl_add_u64 v[58:59], v[12:13], 0, s[12:13]
	v_lshlrev_b32_e32 v4, 11, v3
	s_waitcnt lgkmcnt(6)
	v_cvt_pk_bf16_f32 v28, v34, v32
	s_waitcnt lgkmcnt(4)
	v_cvt_pk_bf16_f32 v29, v36, v38
	s_waitcnt lgkmcnt(2)
	v_cvt_pk_bf16_f32 v30, v40, v52
	s_waitcnt lgkmcnt(0)
	v_cvt_pk_bf16_f32 v31, v54, v56
	v_lshl_add_u64 v[60:61], v[58:59], 0, v[4:5]
	global_store_dwordx4 v[60:61], v[28:31], off
	v_or_b32_e32 v3, s3, v47
	v_lshlrev_b32_e32 v4, 11, v3
	v_cvt_pk_bf16_f32 v28, v35, v33
	v_cvt_pk_bf16_f32 v29, v37, v39
	v_cvt_pk_bf16_f32 v30, v41, v53
	v_cvt_pk_bf16_f32 v31, v55, v57
	ds_read2_b32 v[34:35], v46 offset0:49 offset1:57
	ds_read2_b32 v[36:37], v46 offset0:16 offset1:24
	ds_read2_b32 v[38:39], v46 offset0:82 offset1:90
	ds_read2_b32 v[40:41], v46 offset0:115 offset1:123
	ds_read2_b32 v[52:53], v46 offset0:148 offset1:156
	ds_read2_b32 v[54:55], v46 offset0:181 offset1:189
	ds_read2_b32 v[56:57], v46 offset0:214 offset1:222
	ds_read2_b32 v[60:61], v46 offset0:247 offset1:255
	v_or_b32_e32 v3, s3, v48
	v_lshl_add_u64 v[32:33], v[58:59], 0, v[4:5]
	v_lshlrev_b32_e32 v4, 11, v3
	v_or_b32_e32 v3, s3, v49
	global_store_dwordx4 v[32:33], v[28:31], off
	v_lshl_add_u64 v[32:33], v[58:59], 0, v[4:5]
	v_lshlrev_b32_e32 v4, 11, v3
	s_waitcnt lgkmcnt(6)
	v_cvt_pk_bf16_f32 v28, v36, v34
	s_waitcnt lgkmcnt(4)
	v_cvt_pk_bf16_f32 v29, v38, v40
	s_waitcnt lgkmcnt(2)
	v_cvt_pk_bf16_f32 v30, v52, v54
	s_waitcnt lgkmcnt(0)
	v_cvt_pk_bf16_f32 v31, v56, v60
	global_store_dwordx4 v[32:33], v[28:31], off
	v_lshl_add_u64 v[32:33], v[58:59], 0, v[4:5]
	s_nop 0
	v_cvt_pk_bf16_f32 v28, v37, v35
	v_cvt_pk_bf16_f32 v29, v39, v41
	v_cvt_pk_bf16_f32 v30, v53, v55
	v_cvt_pk_bf16_f32 v31, v57, v61
	global_store_dwordx4 v[32:33], v[28:31], off
	s_waitcnt lgkmcnt(0)

; #define LAS __attribute__((address_space(3)))
; __device__ __forceinline__ void p0_transpose_item(const float* W, int K, int N, u16* WT, LAS float* scr, int item, int lane, const float* gk = nullptr, const float* bk = nullptr, float* c1 = nullptr, float* c2 = nullptr) {
;     const int nblk = N / 32, kb = item / nblk, nb = item % nblk, k0 = 64 * kb, n0 = 32 * nb;
; #pragma unroll 8
;     for (int i = 0; i < 32; ++i) { const int kk = 2 * i + (lane >> 5); scr[kk * 33 + (lane & 31)] = W[(size_t)(k0 + kk) * N + n0 + (lane & 31)]; }
;     asm volatile("s_waitcnt lgkmcnt(0)" ::: "memory");
.LBB0_89:
	s_lshl_b32 s16, s3, 1
	s_lshl_b32 s17, s12, 1
	v_or_b32_e32 v4, s17, v30
	s_add_i32 s30, s16, 4
	s_add_i32 s31, s17, 4
	v_mov_b32_e32 v35, v5
	s_add_i32 s34, s17, 8
	v_lshlrev_b64 v[58:59], 12, v[4:5]
	v_or_b32_e32 v34, s30, v3
	v_or_b32_e32 v4, s31, v30
	v_mov_b32_e32 v33, v5
	v_or_b32_e32 v32, s16, v3
	s_add_i32 s36, s17, 12
	v_lshlrev_b64 v[34:35], 12, v[34:35]
	v_lshlrev_b64 v[60:61], 12, v[4:5]
	v_or_b32_e32 v4, s34, v30
	s_add_i32 s33, s16, 8
	s_add_i32 s35, s16, 12
	s_add_i32 s38, s17, 16
	v_lshlrev_b64 v[32:33], 12, v[32:33]
	v_lshl_add_u64 v[58:59], v[28:29], 0, v[58:59]
	v_lshl_add_u64 v[34:35], v[28:29], 0, v[34:35]
	v_lshlrev_b64 v[62:63], 12, v[4:5]
	v_or_b32_e32 v4, s36, v30
	v_mov_b32_e32 v37, v5
	v_mov_b32_e32 v39, v5
	s_add_i32 s40, s17, 20
	v_or_b32_e32 v36, s33, v3
	v_or_b32_e32 v38, s35, v3
	v_lshl_add_u64 v[32:33], v[28:29], 0, v[32:33]
	v_lshl_add_u64 v[60:61], v[28:29], 0, v[60:61]
	global_load_dword v27, v[58:59], off nt
	global_load_dword v31, v[32:33], off nt
	global_load_dword v74, v[60:61], off nt
	global_load_dword v75, v[34:35], off nt
	v_lshlrev_b64 v[34:35], 12, v[4:5]
	v_or_b32_e32 v4, s38, v30
	s_add_i32 s37, s16, 16
	s_add_i32 s39, s16, 20
	s_add_i32 s42, s17, 24
	v_lshlrev_b64 v[36:37], 12, v[36:37]
	v_lshlrev_b64 v[38:39], 12, v[38:39]
	v_lshl_add_u64 v[32:33], v[28:29], 0, v[62:63]
	v_lshl_add_u64 v[34:35], v[28:29], 0, v[34:35]
	v_lshlrev_b64 v[58:59], 12, v[4:5]
	v_or_b32_e32 v4, s40, v30
	v_mov_b32_e32 v41, v5
	v_mov_b32_e32 v53, v5
	s_add_i32 s41, s16, 24
	s_add_i32 s43, s16, 28
	s_add_i32 s44, s17, 28
	v_or_b32_e32 v40, s37, v3
	v_or_b32_e32 v52, s39, v3
	v_lshl_add_u64 v[36:37], v[28:29], 0, v[36:37]
	v_lshl_add_u64 v[38:39], v[28:29], 0, v[38:39]
	global_load_dword v76, v[32:33], off nt
	global_load_dword v77, v[36:37], off nt
	global_load_dword v78, v[34:35], off nt
	global_load_dword v79, v[38:39], off nt
	v_lshlrev_b64 v[34:35], 12, v[4:5]
	v_or_b32_e32 v4, s42, v30
	v_mov_b32_e32 v55, v5
	v_mov_b32_e32 v57, v5
	v_or_b32_e32 v54, s41, v3
	v_or_b32_e32 v56, s43, v3
	v_lshlrev_b64 v[40:41], 12, v[40:41]
	v_lshlrev_b64 v[52:53], 12, v[52:53]
	v_lshl_add_u64 v[32:33], v[28:29], 0, v[58:59]
	v_lshl_add_u64 v[34:35], v[28:29], 0, v[34:35]
	v_lshlrev_b64 v[36:37], 12, v[4:5]
	v_or_b32_e32 v4, s44, v30
	v_lshlrev_b64 v[54:55], 12, v[54:55]
	v_lshlrev_b64 v[56:57], 12, v[56:57]
	v_lshl_add_u64 v[40:41], v[28:29], 0, v[40:41]
	v_lshl_add_u64 v[52:53], v[28:29], 0, v[52:53]
	global_load_dword v80, v[32:33], off nt
	global_load_dword v81, v[40:41], off nt
	global_load_dword v82, v[34:35], off nt
	global_load_dword v83, v[52:53], off nt
	v_lshl_add_u64 v[32:33], v[28:29], 0, v[36:37]
	v_lshlrev_b64 v[34:35], 12, v[4:5]
	v_lshl_add_u64 v[54:55], v[28:29], 0, v[54:55]
	v_lshl_add_u64 v[56:57], v[28:29], 0, v[56:57]
	v_lshl_add_u64 v[34:35], v[28:29], 0, v[34:35]
	global_load_dword v4, v[32:33], off nt
	global_load_dword v84, v[54:55], off nt
	global_load_dword v85, v[34:35], off nt
	global_load_dword v86, v[56:57], off nt
	v_or_b32_e32 v34, s16, v1
	v_or_b32_e32 v32, s17, v2
	s_add_i32 s12, s12, 16
	s_add_i32 s3, s3, 16
	s_add_i32 s15, s15, -16
	v_mad_u64_u32 v[32:33], s[16:17], v32, s26, v[6:7]
	v_mad_u64_u32 v[34:35], s[16:17], v34, s26, v[6:7]
	v_or_b32_e32 v33, s30, v1
	v_or_b32_e32 v35, s31, v2
	v_or_b32_e32 v52, s33, v1
	v_or_b32_e32 v40, s34, v2
	v_or_b32_e32 v56, s35, v1
	v_or_b32_e32 v54, s36, v2
	v_or_b32_e32 v60, s37, v1
	v_or_b32_e32 v58, s38, v2
	v_or_b32_e32 v64, s39, v1
	v_or_b32_e32 v62, s40, v2
	v_or_b32_e32 v68, s41, v1
	v_or_b32_e32 v66, s42, v2
	v_or_b32_e32 v72, s43, v1
	v_or_b32_e32 v70, s44, v2
	s_cmp_lg_u32 s15, 0
	v_mad_u64_u32 v[36:37], s[16:17], v35, s26, v[6:7]
	v_mad_u64_u32 v[38:39], s[16:17], v33, s26, v[6:7]
	v_mad_u64_u32 v[40:41], s[16:17], v40, s26, v[6:7]
	v_mad_u64_u32 v[52:53], s[16:17], v52, s26, v[6:7]
	v_mad_u64_u32 v[54:55], s[16:17], v54, s26, v[6:7]
	v_mad_u64_u32 v[56:57], s[16:17], v56, s26, v[6:7]
	v_mad_u64_u32 v[58:59], s[16:17], v58, s26, v[6:7]
	v_mad_u64_u32 v[60:61], s[16:17], v60, s26, v[6:7]
	v_mad_u64_u32 v[62:63], s[16:17], v62, s26, v[6:7]
	v_mad_u64_u32 v[64:65], s[16:17], v64, s26, v[6:7]
	v_mad_u64_u32 v[66:67], s[16:17], v66, s26, v[6:7]
	v_mad_u64_u32 v[68:69], s[16:17], v68, s26, v[6:7]
	v_mad_u64_u32 v[70:71], s[16:17], v70, s26, v[6:7]
	v_mad_u64_u32 v[72:73], s[16:17], v72, s26, v[6:7]
	s_waitcnt vmcnt(15)
	ds_write_b32 v32, v27
	s_waitcnt vmcnt(14)
	ds_write_b32 v34, v31
	s_waitcnt vmcnt(13)
	ds_write_b32 v36, v74
	s_waitcnt vmcnt(12)
	ds_write_b32 v38, v75
	s_waitcnt vmcnt(11)
	ds_write_b32 v40, v76
	s_waitcnt vmcnt(10)
	ds_write_b32 v52, v77
	s_waitcnt vmcnt(9)
	ds_write_b32 v54, v78
	s_waitcnt vmcnt(8)
	ds_write_b32 v56, v79
	s_waitcnt vmcnt(7)
	ds_write_b32 v58, v80
	s_waitcnt vmcnt(6)
	ds_write_b32 v60, v81
	s_waitcnt vmcnt(5)
	ds_write_b32 v62, v82
	s_waitcnt vmcnt(4)
	ds_write_b32 v64, v83
	s_waitcnt vmcnt(3)
	ds_write_b32 v66, v4
	s_waitcnt vmcnt(2)
	ds_write_b32 v68, v84
	s_waitcnt vmcnt(1)
	ds_write_b32 v70, v85
	s_waitcnt vmcnt(0)
	ds_write_b32 v72, v86
	s_cbranch_scc1 .LBB0_89
; #define LAS __attribute__((address_space(3)))
; __device__ __forceinline__ unsigned pk2(float lo, float hi) { f32x2_t v = {lo, hi}; bf16x2_t b = __builtin_convertvector(v, bf16x2_t); return __builtin_bit_cast(unsigned, b); }
; __device__ __forceinline__ void p0_transpose_item(const float* W, int K, int N, u16* WT, LAS float* scr, int item, int lane, const float* gk = nullptr, const float* bk = nullptr, float* c1 = nullptr, float* c2 = nullptr) {
;     ...
; #pragma unroll
;     for (int j = 0; j < 4; ++j) { const int n = (lane >> 3) + 8 * j; const LAS float* sp = scr + (8 * c) * 33 + n;
;         v4u o; o.x = pk2(sp[0 * 33] * gs[0], sp[1 * 33] * gs[1]); o.y = pk2(sp[2 * 33] * gs[2], sp[3 * 33] * gs[3]); o.z = pk2(sp[4 * 33] * gs[4], sp[5 * 33] * gs[5]); o.w = pk2(sp[6 * 33] * gs[6], sp[7 * 33] * gs[7]);
;         *(v4u*)(WT + (size_t)(n0 + n) * K + k0 + 8 * c) = o; }
;     asm volatile("s_waitcnt lgkmcnt(0)" ::: "memory");
	s_waitcnt lgkmcnt(0)
	ds_read2_b32 v[32:33], v46 offset0:33 offset1:41
	ds_read2_b32 v[34:35], v46 offset1:8
	ds_read2_b32 v[36:37], v46 offset0:66 offset1:74
	ds_read2_b32 v[38:39], v46 offset0:99 offset1:107
	ds_read2_b32 v[40:41], v46 offset0:132 offset1:140
	ds_read2_b32 v[52:53], v46 offset0:165 offset1:173
	ds_read2_b32 v[54:55], v46 offset0:198 offset1:206
	ds_read2_b32 v[56:57], v46 offset0:231 offset1:239
	s_lshl_b32 s12, s14, 1
	v_or_b32_e32 v3, s2, v45
	v_lshl_add_u64 v[58:59], v[14:15], 0, s[12:13]
	v_lshlrev_b32_e32 v4, 11, v3
	s_waitcnt lgkmcnt(6)
	v_cvt_pk_bf16_f32 v28, v34, v32
	s_waitcnt lgkmcnt(4)
	v_cvt_pk_bf16_f32 v29, v36, v38
	s_waitcnt lgkmcnt(2)
	v_cvt_pk_bf16_f32 v30, v40, v52
	s_waitcnt lgkmcnt(0)
	v_cvt_pk_bf16_f32 v31, v54, v56
	v_lshl_add_u64 v[60:61], v[58:59], 0, v[4:5]
	global_store_dwordx4 v[60:61], v[28:31], off
	v_or_b32_e32 v3, s2, v47
	v_lshlrev_b32_e32 v4, 11, v3
	v_cvt_pk_bf16_f32 v28, v35, v33
	v_cvt_pk_bf16_f32 v29, v37, v39
	v_cvt_pk_bf16_f32 v30, v41, v53
	v_cvt_pk_bf16_f32 v31, v55, v57
	ds_read2_b32 v[34:35], v46 offset0:49 offset1:57
	ds_read2_b32 v[36:37], v46 offset0:16 offset1:24
	ds_read2_b32 v[38:39], v46 offset0:82 offset1:90
	ds_read2_b32 v[40:41], v46 offset0:115 offset1:123
	ds_read2_b32 v[52:53], v46 offset0:148 offset1:156
	ds_read2_b32 v[54:55], v46 offset0:181 offset1:189
	ds_read2_b32 v[56:57], v46 offset0:214 offset1:222
	ds_read2_b32 v[60:61], v46 offset0:247 offset1:255
	v_or_b32_e32 v3, s2, v48
	v_lshl_add_u64 v[32:33], v[58:59], 0, v[4:5]
	v_lshlrev_b32_e32 v4, 11, v3
	v_or_b32_e32 v3, s2, v49
	global_store_dwordx4 v[32:33], v[28:31], off
	v_lshl_add_u64 v[32:33], v[58:59], 0, v[4:5]
	v_lshlrev_b32_e32 v4, 11, v3
	s_waitcnt lgkmcnt(6)
	v_cvt_pk_bf16_f32 v28, v36, v34
	s_waitcnt lgkmcnt(4)
	v_cvt_pk_bf16_f32 v29, v38, v40
	s_waitcnt lgkmcnt(2)
	v_cvt_pk_bf16_f32 v30, v52, v54
	s_waitcnt lgkmcnt(0)
	v_cvt_pk_bf16_f32 v31, v56, v60
	global_store_dwordx4 v[32:33], v[28:31], off
	v_lshl_add_u64 v[32:33], v[58:59], 0, v[4:5]
	s_nop 0
	v_cvt_pk_bf16_f32 v28, v37, v35
	v_cvt_pk_bf16_f32 v29, v39, v41
	v_cvt_pk_bf16_f32 v30, v53, v55
	v_cvt_pk_bf16_f32 v31, v57, v61
	global_store_dwordx4 v[32:33], v[28:31], off
	s_waitcnt lgkmcnt(0)

; #define LAS __attribute__((address_space(3)))
; __device__ __forceinline__ void p0_transpose_item(const float* W, int K, int N, u16* WT, LAS float* scr, int item, int lane, const float* gk = nullptr, const float* bk = nullptr, float* c1 = nullptr, float* c2 = nullptr) {
;     const int nblk = N / 32, kb = item / nblk, nb = item % nblk, k0 = 64 * kb, n0 = 32 * nb;
; #pragma unroll 8
;     for (int i = 0; i < 32; ++i) { const int kk = 2 * i + (lane >> 5); scr[kk * 33 + (lane & 31)] = W[(size_t)(k0 + kk) * N + n0 + (lane & 31)]; }
;     asm volatile("s_waitcnt lgkmcnt(0)" ::: "memory");
;     const int c = lane & 7;
;     float gs[8];
; #pragma unroll
;     for (int e = 0; e < 8; ++e) gs[e] = gk ? gk[k0 + 8 * c + e] : 1.f;
;     if (gk) {
;         const int n = lane & 31, kh = (lane >> 5) * 32; float s1 = 0.f, s2 = 0.f;
; #pragma unroll 8
;         for (int kk = 0; kk < 32; ++kk) { const float wv = scr[(kh + kk) * 33 + n]; s1 += gk[k0 + kh + kk] * wv; s2 += bk[k0 + kh + kk] * wv; }
;         s1 += shx(s1, 32, lane); s2 += shx(s2, 32, lane);
;         if (lane < 32) { atomicAdd(c1 + n0 + n, s1); atomicAdd(c2 + n0 + n, s2); }
;     }
; #pragma unroll
;     for (int j = 0; j < 4; ++j) { const int n = (lane >> 3) + 8 * j; const LAS float* sp = scr + (8 * c) * 33 + n;
;         v4u o; o.x = pk2(sp[0 * 33] * gs[0], sp[1 * 33] * gs[1]); o.y = pk2(sp[2 * 33] * gs[2], sp[3 * 33] * gs[3]); o.z = pk2(sp[4 * 33] * gs[4], sp[5 * 33] * gs[5]); o.w = pk2(sp[6 * 33] * gs[6], sp[7 * 33] * gs[7]);
;         *(v4u*)(WT + (size_t)(n0 + n) * K + k0 + 8 * c) = o; }
;     asm volatile("s_waitcnt lgkmcnt(0)" ::: "memory");
; __device__ __forceinline__ void prologue(const Args& A, LAS unsigned char* lds, int gw, int NGW, int wave, int lane) {
;     ...
;     for (int it = gw; it < total; it += NGW) {
;         int r = it;
;         if (r < cnt[0]) { p0_transpose_item(A.ev_w_in, 1024, NIN0, (u16*)(ws + WS_WIN0), scr, r, lane); continue; } r -= cnt[0];
;         if (r < cnt[1]) { p0_transpose_item(A.ev_w_out, 1024, 1024, (u16*)(ws + WS_WOUT0), scr, r, lane); continue; } r -= cnt[1];
;         if (r < cnt[2]) { p0_transpose_item(A.od_w_in, 1024, NIN1, (u16*)(ws + WS_WIN1), scr, r, lane); continue; } r -= cnt[2];
;         if (r < cnt[3]) { p0_transpose_item(A.od_w_out, 1024, 1024, (u16*)(ws + WS_WOUT1), scr, r, lane); continue; } r -= cnt[3];
.LBB0_94:
	s_lshl_b32 s30, s3, 1
	s_lshl_b32 s31, s12, 1
	v_or_b32_e32 v27, s30, v3
	v_or_b32_e32 v30, s31, v4
	s_add_i32 s33, s30, 4
	s_add_i32 s34, s31, 4
	s_add_i32 s35, s30, 8
	s_add_i32 s36, s31, 8
	s_add_i32 s37, s30, 12
	s_add_i32 s38, s31, 12
	s_add_i32 s39, s30, 16
	s_add_i32 s40, s31, 16
	s_add_i32 s41, s30, 20
	s_add_i32 s42, s31, 20
	s_add_i32 s43, s30, 24
	s_add_i32 s44, s31, 24
	s_add_i32 s45, s30, 28
	s_add_i32 s46, s31, 28
	v_mad_i64_i32 v[30:31], s[16:17], v30, s28, v[28:29]
	v_mad_i64_i32 v[32:33], s[16:17], v27, s28, v[28:29]
	v_or_b32_e32 v27, s33, v3
	v_or_b32_e32 v34, s34, v4
	v_or_b32_e32 v40, s35, v3
	v_or_b32_e32 v38, s36, v4
	v_or_b32_e32 v54, s37, v3
	v_or_b32_e32 v52, s38, v4
	v_or_b32_e32 v58, s39, v3
	v_or_b32_e32 v56, s40, v4
	v_or_b32_e32 v62, s41, v3
	v_or_b32_e32 v60, s42, v4
	v_or_b32_e32 v66, s43, v3
	v_or_b32_e32 v64, s44, v4
	v_or_b32_e32 v70, s45, v3
	v_or_b32_e32 v68, s46, v4
	v_mad_i64_i32 v[34:35], s[16:17], v34, s28, v[28:29]
	v_mad_i64_i32 v[36:37], s[16:17], v27, s28, v[28:29]
	v_mad_i64_i32 v[38:39], s[16:17], v38, s28, v[28:29]
	v_mad_i64_i32 v[40:41], s[16:17], v40, s28, v[28:29]
	v_mad_i64_i32 v[52:53], s[16:17], v52, s28, v[28:29]
	v_mad_i64_i32 v[54:55], s[16:17], v54, s28, v[28:29]
	v_mad_i64_i32 v[56:57], s[16:17], v56, s28, v[28:29]
	v_mad_i64_i32 v[58:59], s[16:17], v58, s28, v[28:29]
	v_mad_i64_i32 v[60:61], s[16:17], v60, s28, v[28:29]
	v_mad_i64_i32 v[62:63], s[16:17], v62, s28, v[28:29]
	v_mad_i64_i32 v[64:65], s[16:17], v64, s28, v[28:29]
	v_mad_i64_i32 v[66:67], s[16:17], v66, s28, v[28:29]
	v_mad_i64_i32 v[68:69], s[16:17], v68, s28, v[28:29]
	v_mad_i64_i32 v[70:71], s[16:17], v70, s28, v[28:29]
	global_load_dword v27, v[30:31], off nt
	global_load_dword v72, v[32:33], off nt
	global_load_dword v73, v[34:35], off nt
	global_load_dword v74, v[36:37], off nt
	global_load_dword v75, v[38:39], off nt
	global_load_dword v76, v[40:41], off nt
	global_load_dword v77, v[52:53], off nt
	global_load_dword v78, v[54:55], off nt
	global_load_dword v79, v[56:57], off nt
	global_load_dword v80, v[58:59], off nt
	global_load_dword v81, v[60:61], off nt
	global_load_dword v82, v[62:63], off nt
	global_load_dword v83, v[64:65], off nt
	global_load_dword v84, v[66:67], off nt
	global_load_dword v85, v[68:69], off nt
	global_load_dword v86, v[70:71], off nt
	v_or_b32_e32 v32, s30, v1
	v_or_b32_e32 v30, s31, v2
	s_add_i32 s12, s12, 16
	s_add_i32 s3, s3, 16
	s_add_i32 s15, s15, -16
	v_mad_u64_u32 v[30:31], s[16:17], v30, s26, v[6:7]
	v_mad_u64_u32 v[32:33], s[16:17], v32, s26, v[6:7]
	v_or_b32_e32 v31, s33, v1
	v_or_b32_e32 v33, s34, v2
	v_or_b32_e32 v40, s35, v1
	v_or_b32_e32 v38, s36, v2
	v_or_b32_e32 v54, s37, v1
	v_or_b32_e32 v52, s38, v2
	v_or_b32_e32 v58, s39, v1
	v_or_b32_e32 v56, s40, v2
	v_or_b32_e32 v62, s41, v1
	v_or_b32_e32 v60, s42, v2
	v_or_b32_e32 v66, s43, v1
	v_or_b32_e32 v64, s44, v2
	v_or_b32_e32 v70, s45, v1
	v_or_b32_e32 v68, s46, v2
	s_cmp_lg_u32 s15, 0
	v_mad_u64_u32 v[34:35], s[16:17], v33, s26, v[6:7]
	v_mad_u64_u32 v[36:37], s[16:17], v31, s26, v[6:7]
	v_mad_u64_u32 v[38:39], s[16:17], v38, s26, v[6:7]
	v_mad_u64_u32 v[40:41], s[16:17], v40, s26, v[6:7]
	v_mad_u64_u32 v[52:53], s[16:17], v52, s26, v[6:7]
	v_mad_u64_u32 v[54:55], s[16:17], v54, s26, v[6:7]
	v_mad_u64_u32 v[56:57], s[16:17], v56, s26, v[6:7]
	v_mad_u64_u32 v[58:59], s[16:17], v58, s26, v[6:7]
	v_mad_u64_u32 v[60:61], s[16:17], v60, s26, v[6:7]
	v_mad_u64_u32 v[62:63], s[16:17], v62, s26, v[6:7]
	v_mad_u64_u32 v[64:65], s[16:17], v64, s26, v[6:7]
	v_mad_u64_u32 v[66:67], s[16:17], v66, s26, v[6:7]
	v_mad_u64_u32 v[68:69], s[16:17], v68, s26, v[6:7]
	v_mad_u64_u32 v[70:71], s[16:17], v70, s26, v[6:7]
	s_waitcnt vmcnt(15)
	ds_write_b32 v30, v27
	s_waitcnt vmcnt(14)
	ds_write_b32 v32, v72
	s_waitcnt vmcnt(13)
	ds_write_b32 v34, v73
	s_waitcnt vmcnt(12)
	ds_write_b32 v36, v74
	s_waitcnt vmcnt(11)
	ds_write_b32 v38, v75
	s_waitcnt vmcnt(10)
	ds_write_b32 v40, v76
	s_waitcnt vmcnt(9)
	ds_write_b32 v52, v77
	s_waitcnt vmcnt(8)
	ds_write_b32 v54, v78
	s_waitcnt vmcnt(7)
	ds_write_b32 v56, v79
	s_waitcnt vmcnt(6)
	ds_write_b32 v58, v80
	s_waitcnt vmcnt(5)
	ds_write_b32 v60, v81
	s_waitcnt vmcnt(4)
	ds_write_b32 v62, v82
	s_waitcnt vmcnt(3)
	ds_write_b32 v64, v83
	s_waitcnt vmcnt(2)
	ds_write_b32 v66, v84
	s_waitcnt vmcnt(1)
	ds_write_b32 v68, v85
	s_waitcnt vmcnt(0)
	ds_write_b32 v70, v86
	s_cbranch_scc1 .LBB0_94
	s_waitcnt lgkmcnt(0)
	ds_read2_b32 v[32:33], v46 offset0:33 offset1:41
	ds_read2_b32 v[34:35], v46 offset1:8
	ds_read2_b32 v[36:37], v46 offset0:66 offset1:74
	ds_read2_b32 v[38:39], v46 offset0:99 offset1:107
	ds_read2_b32 v[40:41], v46 offset0:132 offset1:140
	ds_read2_b32 v[52:53], v46 offset0:165 offset1:173
	ds_read2_b32 v[54:55], v46 offset0:198 offset1:206
	ds_read2_b32 v[56:57], v46 offset0:231 offset1:239
	v_or_b32_e32 v60, s2, v45
	s_ashr_i32 s15, s14, 31
	v_ashrrev_i32_e32 v61, 31, v60
	v_lshl_add_u64 v[58:59], s[14:15], 1, v[16:17]
	v_lshlrev_b64 v[60:61], 11, v[60:61]
	s_waitcnt lgkmcnt(6)
	v_cvt_pk_bf16_f32 v28, v34, v32
	s_waitcnt lgkmcnt(4)
	v_cvt_pk_bf16_f32 v29, v36, v38
	s_waitcnt lgkmcnt(2)
	v_cvt_pk_bf16_f32 v30, v40, v52
	s_waitcnt lgkmcnt(0)
	v_cvt_pk_bf16_f32 v31, v54, v56
	v_lshl_add_u64 v[60:61], v[58:59], 0, v[60:61]
	v_or_b32_e32 v32, s2, v47
	global_store_dwordx4 v[60:61], v[28:31], off
	s_nop 1
	v_cvt_pk_bf16_f32 v28, v35, v33
	v_ashrrev_i32_e32 v33, 31, v32
	v_cvt_pk_bf16_f32 v29, v37, v39
	v_cvt_pk_bf16_f32 v30, v41, v53
	v_cvt_pk_bf16_f32 v31, v55, v57
	v_lshlrev_b64 v[32:33], 11, v[32:33]
	ds_read2_b32 v[34:35], v46 offset0:49 offset1:57
	ds_read2_b32 v[36:37], v46 offset0:16 offset1:24
	ds_read2_b32 v[38:39], v46 offset0:82 offset1:90
	ds_read2_b32 v[40:41], v46 offset0:115 offset1:123
	ds_read2_b32 v[52:53], v46 offset0:148 offset1:156
	ds_read2_b32 v[54:55], v46 offset0:181 offset1:189
	ds_read2_b32 v[56:57], v46 offset0:214 offset1:222
	ds_read2_b32 v[60:61], v46 offset0:247 offset1:255
	v_lshl_add_u64 v[32:33], v[58:59], 0, v[32:33]
	global_store_dwordx4 v[32:33], v[28:31], off
	v_or_b32_e32 v32, s2, v48
	v_ashrrev_i32_e32 v33, 31, v32
	v_lshlrev_b64 v[32:33], 11, v[32:33]
	s_waitcnt lgkmcnt(6)
	v_cvt_pk_bf16_f32 v28, v36, v34
	s_waitcnt lgkmcnt(4)
	v_cvt_pk_bf16_f32 v29, v38, v40
	s_waitcnt lgkmcnt(2)
	v_cvt_pk_bf16_f32 v30, v52, v54
	s_waitcnt lgkmcnt(0)
	v_cvt_pk_bf16_f32 v31, v56, v60
	v_lshl_add_u64 v[32:33], v[58:59], 0, v[32:33]
	global_store_dwordx4 v[32:33], v[28:31], off
	v_or_b32_e32 v32, s2, v49
	v_ashrrev_i32_e32 v33, 31, v32
	v_lshlrev_b64 v[32:33], 11, v[32:33]
	v_cvt_pk_bf16_f32 v28, v37, v35
	v_cvt_pk_bf16_f32 v29, v39, v41
	v_cvt_pk_bf16_f32 v30, v53, v55
	v_cvt_pk_bf16_f32 v31, v57, v61
	v_lshl_add_u64 v[32:33], v[58:59], 0, v[32:33]
	global_store_dwordx4 v[32:33], v[28:31], off
	s_waitcnt lgkmcnt(0)
	s_branch .LBB0_7

; __device__ __forceinline__ unsigned pk2(float lo, float hi) { f32x2_t v = {lo, hi}; bf16x2_t b = __builtin_convertvector(v, bf16x2_t); return __builtin_bit_cast(unsigned, b); }
; __device__ __forceinline__ void prologue(const Args& A, LAS unsigned char* lds, int gw, int NGW, int wave, int lane) {
;     ...
;     for (int m = gw; m < MTOK; m += NGW) {
;         const f32x4* xr = (const f32x4*)(A.x + (size_t)m * 1024) + 2 * lane; v4u* o = (v4u*)(XB + (size_t)m * 1024) + lane;
; #pragma unroll
;         for (int j = 0; j < 2; ++j) { const f32x4 v = xr[128 * j], v2 = xr[128 * j + 1]; v4u w; w.x = pk2(v[0], v[1]); w.y = pk2(v[2], v[3]); w.z = pk2(v2[0], v2[1]); w.w = pk2(v2[2], v2[3]); o[64 * j] = w; }
;     }
.LBB0_98:
	global_load_dwordx4 v[10:13], v[4:5], off nt
	global_load_dwordx4 v[14:17], v[4:5], off offset:16 nt
	s_add_i32 s8, s8, s52
	s_cmpk_gt_i32 s8, 0x7fff
	s_waitcnt vmcnt(1)
	v_cvt_pk_bf16_f32 v10, v10, v11
	v_cvt_pk_bf16_f32 v11, v12, v13
	s_waitcnt vmcnt(0)
	v_cvt_pk_bf16_f32 v12, v14, v15
	v_cvt_pk_bf16_f32 v13, v16, v17
	global_store_dwordx4 v[2:3], v[10:13], off offset:-1024
	global_load_dwordx4 v[10:13], v[4:5], off offset:2048 nt
	s_nop 0
	global_load_dwordx4 v[14:17], v[4:5], off offset:2064 nt
	v_lshl_add_u64 v[4:5], v[4:5], 0, s[2:3]
	s_waitcnt vmcnt(1)
	v_cvt_pk_bf16_f32 v10, v10, v11
	v_cvt_pk_bf16_f32 v11, v12, v13
	s_waitcnt vmcnt(0)
	v_cvt_pk_bf16_f32 v12, v14, v15
	v_cvt_pk_bf16_f32 v13, v16, v17
	global_store_dwordx4 v[2:3], v[10:13], off
	v_lshl_add_u64 v[2:3], v[2:3], 0, s[0:1]
	s_cbranch_scc0 .LBB0_98

; __device__ __forceinline__ void prologue(const Args& A, LAS unsigned char* lds, int gw, int NGW, int wave, int lane) {
;     ...
;     for (int i = gw * 64 + lane; i < 512; i += NGW * 64) { const float l0 = A.hg_lb_logits[i], l1 = A.hg_lb_logits[512 + i]; misc[i] = 1.f / (1.f + __expf(l1 - l0)); }
.LBB0_113:
	v_lshl_add_u64 v[4:5], s[76:77], 0, v[2:3]
	global_load_dword v1, v[4:5], off nt
	global_load_dword v7, v[4:5], off offset:2048 nt
	v_add_u32_e32 v10, s26, v10
	v_cmp_lt_i32_e32 vcc, s10, v10
	s_or_b64 s[8:9], vcc, s[8:9]
	v_lshl_add_u64 v[4:5], s[50:51], 0, v[2:3]
	v_lshl_add_u64 v[2:3], v[2:3], 0, s[2:3]
	s_waitcnt vmcnt(0)
	v_sub_f32_e32 v1, v7, v1
	v_mul_f32_e32 v1, 0x3fb8aa3b, v1
	v_exp_f32_e32 v1, v1
	s_nop 0
	v_add_f32_e32 v1, 1.0, v1
	v_div_scale_f32 v7, s[12:13], v1, v1, 1.0
	v_rcp_f32_e32 v9, v7
	v_div_scale_f32 v11, vcc, 1.0, v1, 1.0
	v_fma_f32 v12, -v7, v9, 1.0
	v_fmac_f32_e32 v9, v12, v9
	v_mul_f32_e32 v12, v11, v9
	v_fma_f32 v13, -v7, v12, v11
	v_fmac_f32_e32 v12, v13, v9
	v_fma_f32 v7, -v7, v12, v11
	v_div_fmas_f32 v7, v7, v9, v12
	v_div_fixup_f32 v1, v7, v1, 1.0
	global_store_dword v[4:5], v1, off
	s_andn2_b64 exec, exec, s[8:9]
	s_cbranch_execnz .LBB0_113

; __device__ __forceinline__ unsigned pk2(float lo, float hi) { f32x2_t v = {lo, hi}; bf16x2_t b = __builtin_convertvector(v, bf16x2_t); return __builtin_bit_cast(unsigned, b); }
; __device__ __forceinline__ void p_rows2(const float* prow, u16* PBo, int gw, int NGW, int lane) {
;     for (int m = gw; m < 2 * MTOK; m += NGW) {
;         if (lane < 32) { const f32x4 a = ((const f32x4*)(prow + (size_t)m * 256))[2 * lane], b = ((const f32x4*)(prow + (size_t)m * 256))[2 * lane + 1];
;             v4u w; w.x = pk2(a[0], a[1]); w.y = pk2(a[2], a[3]); w.z = pk2(b[0], b[1]); w.w = pk2(b[2], b[3]); ((v4u*)(PBo + (size_t)m * 256))[lane] = w; }
;     }
.LBB0_117:
	s_and_saveexec_b64 s[8:9], vcc
	s_cbranch_execz .LBB0_116
	global_load_dwordx4 v[6:9], v[2:3], off offset:-16 nt
	global_load_dwordx4 v[10:13], v[2:3], off nt
	s_waitcnt vmcnt(1)
	v_cvt_pk_bf16_f32 v6, v6, v7
	v_cvt_pk_bf16_f32 v7, v8, v9
	s_waitcnt vmcnt(0)
	v_cvt_pk_bf16_f32 v8, v10, v11
	v_cvt_pk_bf16_f32 v9, v12, v13
	global_store_dwordx4 v[4:5], v[6:9], off
	s_branch .LBB0_116

; __device__ __forceinline__ unsigned pk2(float lo, float hi) { f32x2_t v = {lo, hi}; bf16x2_t b = __builtin_convertvector(v, bf16x2_t); return __builtin_bit_cast(unsigned, b); }
; __device__ __forceinline__ float bflo(unsigned w) { return __uint_as_float(w << 16); }
; __device__ __forceinline__ float bfhi(unsigned w) { return __uint_as_float(w & 0xffff0000u); }
; __device__ __forceinline__ void dil_merge(const u16* OB0, const u16* OB1, const u16* OB2, const float* LSE, u16* MIX, int gw, int NGW, int lane) {
;     const int hd = lane >> 2, dq = (lane & 3) * 16;
;     for (int m = gw; m < MTOK; m += NGW) {
;         const float l0 = LSE[((size_t)m) * 16 + hd], l1 = LSE[((size_t)MTOK + m) * 16 + hd], l2 = LSE[((size_t)2 * MTOK + m) * 16 + hd];
;         const float mx = fmaxf(l0, fmaxf(l1, l2)); float w0 = __expf(l0 - mx), w1 = __expf(l1 - mx), w2 = __expf(l2 - mx); const float iz = 1.f / (w0 + w1 + w2); w0 *= iz; w1 *= iz; w2 *= iz;
;         const size_t off = (size_t)m * 1024 + hd * 64 + dq;
; #pragma unroll
;         for (int j = 0; j < 2; ++j) { const v4u a = *(const v4u*)(OB0 + off + 8 * j), bq = *(const v4u*)(OB1 + off + 8 * j), c = *(const v4u*)(OB2 + off + 8 * j);
;             const unsigned aw[4] = {a.x, a.y, a.z, a.w}, bw[4] = {bq.x, bq.y, bq.z, bq.w}, cw[4] = {c.x, c.y, c.z, c.w}; unsigned ow[4];
; #pragma unroll
;             for (int e = 0; e < 4; ++e) ow[e] = pk2(w0 * bflo(aw[e]) + w1 * bflo(bw[e]) + w2 * bflo(cw[e]), w0 * bfhi(aw[e]) + w1 * bfhi(bw[e]) + w2 * bfhi(cw[e]));
;             *(v4u*)(MIX + off + 8 * j) = (v4u){ow[0], ow[1], ow[2], ow[3]}; }
;     }
.LBB0_509:
	s_nop 0
	v_lshl_add_u64 v[6:7], s[62:63], 0, v[4:5]
	v_add_co_u32_e32 v8, vcc, 0x3800000, v6
	v_lshl_add_u64 v[34:35], s[62:63], 0, v[2:3]
	s_nop 0
	v_addc_co_u32_e32 v9, vcc, 0, v7, vcc
	global_load_dword v0, v[8:9], off
	v_add_co_u32_e32 v8, vcc, 0x3a00000, v6
	s_brev_b32 s1, 56
	s_nop 0
	v_addc_co_u32_e32 v9, vcc, 0, v7, vcc
	v_add_co_u32_e32 v6, vcc, 0x3c00000, v6
	global_load_dword v8, v[8:9], off
	s_nop 0
	v_addc_co_u32_e32 v7, vcc, 0, v7, vcc
	global_load_dword v6, v[6:7], off
	s_add_i32 s0, s0, s4
	v_lshl_add_u64 v[2:3], v[2:3], 0, s[30:31]
	v_lshl_add_u64 v[4:5], v[4:5], 0, s[34:35]
	s_cmp_lt_i32 s0, 0x8000
	s_waitcnt vmcnt(0)
	v_max3_f32 v7, v0, v8, v6
	v_sub_f32_e32 v0, v0, v7
	v_mul_f32_e32 v0, 0x3fb8aa3b, v0
	v_exp_f32_e32 v31, v0
	v_sub_f32_e32 v0, v8, v7
	v_mul_f32_e32 v0, 0x3fb8aa3b, v0
	v_exp_f32_e32 v30, v0
	v_sub_f32_e32 v0, v6, v7
	v_mul_f32_e32 v0, 0x3fb8aa3b, v0
	v_exp_f32_e32 v0, v0
	v_add_f32_e32 v6, v31, v30
	v_add_f32_e32 v6, v0, v6
	v_div_scale_f32 v7, s[2:3], v6, v6, 1.0
	v_rcp_f32_e32 v8, v7
	s_mov_b64 s[2:3], 0x1c000000
	v_fma_f32 v9, -v7, v8, 1.0
	v_fmac_f32_e32 v8, v9, v8
	v_div_scale_f32 v9, vcc, 1.0, v6, 1.0
	v_mul_f32_e32 v10, v9, v8
	v_fma_f32 v11, -v7, v10, v9
	v_fmac_f32_e32 v10, v11, v8
	v_fma_f32 v7, -v7, v10, v9
	v_div_fmas_f32 v7, v7, v8, v10
	v_div_fixup_f32 v32, v7, v6, 1.0
	v_add_co_u32_e32 v6, vcc, s1, v34
	s_brev_b32 s1, 24
	s_nop 0
	v_addc_co_u32_e32 v7, vcc, 0, v35, vcc
	v_lshl_add_u64 v[10:11], v[34:35], 0, s[2:3]
	s_mov_b64 s[2:3], 0x18000000
	v_add_co_u32_e32 v14, vcc, s1, v34
	v_lshl_add_u64 v[18:19], v[34:35], 0, s[2:3]
	s_nop 0
	v_addc_co_u32_e32 v15, vcc, 0, v35, vcc
	s_brev_b32 s1, 32
	s_mov_b64 s[2:3], 0x4000000
	global_load_dwordx4 v[6:9], v[6:7], off nt
	s_nop 0
	global_load_dwordx4 v[10:13], v[10:11], off offset:16 nt
	s_nop 0
	global_load_dwordx4 v[14:17], v[14:15], off nt
	s_nop 0
	global_load_dwordx4 v[18:21], v[18:19], off offset:16 nt
	v_add_co_u32_e32 v22, vcc, s1, v34
	v_lshl_add_u64 v[26:27], v[34:35], 0, s[2:3]
	s_nop 0
	v_addc_co_u32_e32 v23, vcc, 0, v35, vcc
	global_load_dwordx4 v[22:25], v[22:23], off nt
	s_nop 0
	global_load_dwordx4 v[26:29], v[26:27], off offset:16 nt
	v_pk_mul_f32 v[30:31], v[30:31], v[32:33] op_sel_hi:[1,0]
	v_mul_f32_e32 v0, v0, v32
	s_waitcnt vmcnt(5)
	v_lshlrev_b32_e32 v36, 16, v6
	s_waitcnt vmcnt(3)
	v_and_b32_e32 v37, 0xffff0000, v14
	v_lshlrev_b32_e32 v32, 16, v14
	v_and_b32_e32 v33, 0xffff0000, v6
	v_pk_mul_f32 v[36:37], v[30:31], v[36:37] op_sel:[1,0] op_sel_hi:[0,1]
	v_pk_fma_f32 v[32:33], v[30:31], v[32:33], v[36:37]
	v_lshlrev_b32_e32 v14, 16, v7
	s_waitcnt vmcnt(1)
	v_lshlrev_b32_e32 v38, 16, v22
	v_and_b32_e32 v39, 0xffff0000, v22
	v_pk_fma_f32 v[32:33], v[0:1], v[38:39], v[32:33] op_sel_hi:[0,1,1]
	v_cvt_pk_bf16_f32 v6, v32, v33
	v_lshlrev_b32_e32 v32, 16, v15
	v_and_b32_e32 v15, 0xffff0000, v15
	v_and_b32_e32 v33, 0xffff0000, v7
	v_pk_mul_f32 v[14:15], v[30:31], v[14:15] op_sel:[1,0] op_sel_hi:[0,1]
	v_lshlrev_b32_e32 v22, 16, v23
	v_and_b32_e32 v23, 0xffff0000, v23
	v_pk_fma_f32 v[14:15], v[30:31], v[32:33], v[14:15]
	v_lshlrev_b32_e32 v32, 16, v24
	v_pk_fma_f32 v[14:15], v[0:1], v[22:23], v[14:15] op_sel_hi:[0,1,1]
	v_lshlrev_b32_e32 v22, 16, v8
	v_and_b32_e32 v23, 0xffff0000, v16
	v_cvt_pk_bf16_f32 v7, v14, v15
	v_lshlrev_b32_e32 v14, 16, v16
	v_and_b32_e32 v15, 0xffff0000, v8
	v_pk_mul_f32 v[22:23], v[30:31], v[22:23] op_sel:[1,0] op_sel_hi:[0,1]
	v_and_b32_e32 v33, 0xffff0000, v24
	v_pk_fma_f32 v[14:15], v[30:31], v[14:15], v[22:23]
	v_lshlrev_b32_e32 v16, 16, v9
	v_pk_fma_f32 v[14:15], v[0:1], v[32:33], v[14:15] op_sel_hi:[0,1,1]
	v_cvt_pk_bf16_f32 v8, v14, v15
	v_lshlrev_b32_e32 v14, 16, v17
	v_and_b32_e32 v17, 0xffff0000, v17
	v_and_b32_e32 v15, 0xffff0000, v9
	v_pk_mul_f32 v[16:17], v[30:31], v[16:17] op_sel:[1,0] op_sel_hi:[0,1]
	v_pk_fma_f32 v[14:15], v[30:31], v[14:15], v[16:17]
	v_lshlrev_b32_e32 v16, 16, v25
	v_and_b32_e32 v17, 0xffff0000, v25
	v_pk_fma_f32 v[14:15], v[0:1], v[16:17], v[14:15] op_sel_hi:[0,1,1]
	v_cvt_pk_bf16_f32 v9, v14, v15
	v_add_co_u32_e32 v14, vcc, s55, v34
	s_nop 1
	v_addc_co_u32_e32 v15, vcc, 0, v35, vcc
	global_store_dwordx4 v[14:15], v[6:9], off
	s_nop 1
	v_lshlrev_b32_e32 v8, 16, v10
	v_and_b32_e32 v9, 0xffff0000, v18
	v_lshlrev_b32_e32 v6, 16, v18
	v_and_b32_e32 v7, 0xffff0000, v10
	v_pk_mul_f32 v[8:9], v[30:31], v[8:9] op_sel:[1,0] op_sel_hi:[0,1]
	v_pk_fma_f32 v[6:7], v[30:31], v[6:7], v[8:9]
	s_waitcnt vmcnt(1)
	v_lshlrev_b32_e32 v8, 16, v26
	v_and_b32_e32 v9, 0xffff0000, v26
	v_pk_fma_f32 v[6:7], v[0:1], v[8:9], v[6:7] op_sel_hi:[0,1,1]
	v_and_b32_e32 v9, 0xffff0000, v11
	v_lshlrev_b32_e32 v10, 16, v11
	v_and_b32_e32 v11, 0xffff0000, v19
	v_lshlrev_b32_e32 v8, 16, v19
	v_pk_mul_f32 v[10:11], v[30:31], v[10:11] op_sel:[1,0] op_sel_hi:[0,1]
	v_pk_fma_f32 v[8:9], v[30:31], v[8:9], v[10:11]
	v_lshlrev_b32_e32 v10, 16, v27
	v_and_b32_e32 v11, 0xffff0000, v27
	v_pk_fma_f32 v[8:9], v[0:1], v[10:11], v[8:9] op_sel_hi:[0,1,1]
	v_lshlrev_b32_e32 v10, 16, v12
	v_and_b32_e32 v11, 0xffff0000, v20
	v_cvt_pk_bf16_f32 v6, v6, v7
	v_cvt_pk_bf16_f32 v7, v8, v9
	v_lshlrev_b32_e32 v8, 16, v20
	v_and_b32_e32 v9, 0xffff0000, v12
	v_pk_mul_f32 v[10:11], v[30:31], v[10:11] op_sel:[1,0] op_sel_hi:[0,1]
	v_pk_fma_f32 v[8:9], v[30:31], v[8:9], v[10:11]
	v_lshlrev_b32_e32 v10, 16, v28
	v_and_b32_e32 v11, 0xffff0000, v28
	v_pk_fma_f32 v[8:9], v[0:1], v[10:11], v[8:9] op_sel_hi:[0,1,1]
	v_and_b32_e32 v11, 0xffff0000, v13
	v_lshlrev_b32_e32 v12, 16, v13
	v_and_b32_e32 v13, 0xffff0000, v21
	v_lshlrev_b32_e32 v10, 16, v21
	v_pk_mul_f32 v[12:13], v[30:31], v[12:13] op_sel:[1,0] op_sel_hi:[0,1]
	v_pk_fma_f32 v[10:11], v[30:31], v[10:11], v[12:13]
	v_lshlrev_b32_e32 v12, 16, v29
	v_and_b32_e32 v13, 0xffff0000, v29
	v_pk_fma_f32 v[10:11], v[0:1], v[12:13], v[10:11] op_sel_hi:[0,1,1]
	v_cvt_pk_bf16_f32 v8, v8, v9
	v_cvt_pk_bf16_f32 v9, v10, v11
	global_store_dwordx4 v[14:15], v[6:9], off offset:16
	s_cbranch_scc1 .LBB0_509
